# v31 + nt (streaming) policy on the read-once f32 weight loads of phase 0's weight conversion
# speedup vs baseline: 1.0179x; 1.0092x over previous
.LBB0_68:
	v_mul_hi_i32 v6, v5, s14
	v_lshrrev_b32_e32 v7, 31, v6
	v_ashrrev_i32_e32 v6, 5, v6
	v_add_u32_e32 v7, v6, v7
	v_mul_lo_u32 v54, v7, s15
	v_add_u32_e32 v10, v44, v54
	v_mad_u64_u32 v[8:9], s[8:9], v7, s18, v[4:5]
	v_lshlrev_b32_e32 v6, 6, v7
	v_and_b32_e32 v7, 0xffffff80, v8
	v_and_b32_e32 v8, 0x60, v10
	v_or3_b32 v8, v8, v7, v48
	v_and_b32_e32 v7, 4, v5
	v_cmp_eq_u32_e32 vcc, 0, v7
	v_ashrrev_i32_e32 v9, 31, v8
	v_or_b32_e32 v26, v6, v1
	v_cndmask_b32_e32 v11, v45, v51, vcc
	v_cndmask_b32_e32 v10, v52, v53, vcc
	v_lshl_add_u64 v[30:31], v[8:9], 2, v[10:11]
	v_cmp_ne_u64_e32 vcc, 0, v[10:11]
	v_mov_b32_e32 v9, 0
	v_mov_b32_e32 v8, 0
	s_and_saveexec_b64 s[8:9], vcc
	s_cbranch_execz .LBB0_70
	v_mad_i64_i32 v[10:11], s[22:23], v26, s19, v[30:31]
	global_load_dword v8, v[10:11], off nt
.LBB0_70:
	s_or_b64 exec, exec, s[8:9]
	s_and_saveexec_b64 s[8:9], vcc
	s_cbranch_execz .LBB0_72
	v_or_b32_e32 v7, 2, v26
	v_mad_i64_i32 v[10:11], s[22:23], v7, s19, v[30:31]
	global_load_dword v9, v[10:11], off nt
.LBB0_72:
	s_or_b64 exec, exec, s[8:9]
	v_mov_b32_e32 v11, 0
	v_mov_b32_e32 v10, 0
	s_and_saveexec_b64 s[8:9], vcc
	s_cbranch_execz .LBB0_74
	v_or_b32_e32 v7, 4, v26
	v_mad_i64_i32 v[12:13], s[22:23], v7, s19, v[30:31]
	global_load_dword v10, v[12:13], off nt
.LBB0_74:
	s_or_b64 exec, exec, s[8:9]
	s_and_saveexec_b64 s[8:9], vcc
	s_cbranch_execz .LBB0_76
	v_or_b32_e32 v7, 6, v26
	v_mad_i64_i32 v[12:13], s[22:23], v7, s19, v[30:31]
	global_load_dword v11, v[12:13], off nt
.LBB0_76:
	s_or_b64 exec, exec, s[8:9]
	v_mov_b32_e32 v13, 0
	v_mov_b32_e32 v12, 0
	s_and_saveexec_b64 s[8:9], vcc
	s_cbranch_execz .LBB0_78
	v_or_b32_e32 v7, 8, v26
	v_mad_i64_i32 v[14:15], s[22:23], v7, s19, v[30:31]
	global_load_dword v12, v[14:15], off nt
.LBB0_78:
	s_or_b64 exec, exec, s[8:9]
	s_and_saveexec_b64 s[8:9], vcc
	s_cbranch_execz .LBB0_80
	v_or_b32_e32 v7, 10, v26
	v_mad_i64_i32 v[14:15], s[22:23], v7, s19, v[30:31]
	global_load_dword v13, v[14:15], off nt
.LBB0_80:
	s_or_b64 exec, exec, s[8:9]
	v_mov_b32_e32 v15, 0
	v_mov_b32_e32 v14, 0
	s_and_saveexec_b64 s[8:9], vcc
	s_cbranch_execz .LBB0_82
	v_or_b32_e32 v7, 12, v26
	v_mad_i64_i32 v[16:17], s[22:23], v7, s19, v[30:31]
	global_load_dword v14, v[16:17], off nt
.LBB0_82:
	s_or_b64 exec, exec, s[8:9]
	s_and_saveexec_b64 s[8:9], vcc
	s_cbranch_execz .LBB0_84
	v_or_b32_e32 v7, 14, v26
	v_mad_i64_i32 v[16:17], s[22:23], v7, s19, v[30:31]
	global_load_dword v15, v[16:17], off nt
.LBB0_84:
	s_or_b64 exec, exec, s[8:9]
	v_mov_b32_e32 v17, 0
	v_mov_b32_e32 v16, 0
	s_and_saveexec_b64 s[8:9], vcc
	s_cbranch_execz .LBB0_86
	v_or_b32_e32 v7, 16, v26
	v_mad_i64_i32 v[18:19], s[22:23], v7, s19, v[30:31]
	global_load_dword v16, v[18:19], off nt
.LBB0_86:
	s_or_b64 exec, exec, s[8:9]
	s_and_saveexec_b64 s[8:9], vcc
	s_cbranch_execz .LBB0_88
	v_or_b32_e32 v7, 18, v26
	v_mad_i64_i32 v[18:19], s[22:23], v7, s19, v[30:31]
	global_load_dword v17, v[18:19], off nt
.LBB0_88:
	s_or_b64 exec, exec, s[8:9]
	v_mov_b32_e32 v19, 0
	v_mov_b32_e32 v18, 0
	s_and_saveexec_b64 s[8:9], vcc
	s_cbranch_execz .LBB0_90
	v_or_b32_e32 v7, 20, v26
	v_mad_i64_i32 v[20:21], s[22:23], v7, s19, v[30:31]
	global_load_dword v18, v[20:21], off nt
.LBB0_90:
	s_or_b64 exec, exec, s[8:9]
	s_and_saveexec_b64 s[8:9], vcc
	s_cbranch_execz .LBB0_92
	v_or_b32_e32 v7, 22, v26
	v_mad_i64_i32 v[20:21], s[22:23], v7, s19, v[30:31]
	global_load_dword v19, v[20:21], off nt
.LBB0_92:
	s_or_b64 exec, exec, s[8:9]
	v_mov_b32_e32 v21, 0
	v_mov_b32_e32 v20, 0
	s_and_saveexec_b64 s[8:9], vcc
	s_cbranch_execz .LBB0_94
	v_or_b32_e32 v7, 24, v26
	v_mad_i64_i32 v[22:23], s[22:23], v7, s19, v[30:31]
	global_load_dword v20, v[22:23], off nt
.LBB0_94:
	s_or_b64 exec, exec, s[8:9]
	s_and_saveexec_b64 s[8:9], vcc
	s_cbranch_execz .LBB0_96
	v_or_b32_e32 v7, 26, v26
	v_mad_i64_i32 v[22:23], s[22:23], v7, s19, v[30:31]
	global_load_dword v21, v[22:23], off nt
.LBB0_96:
	s_or_b64 exec, exec, s[8:9]
	v_mov_b32_e32 v23, 0
	v_mov_b32_e32 v22, 0
	s_and_saveexec_b64 s[8:9], vcc
	s_cbranch_execz .LBB0_98
	v_or_b32_e32 v7, 28, v26
	v_mad_i64_i32 v[24:25], s[22:23], v7, s19, v[30:31]
	global_load_dword v22, v[24:25], off nt
.LBB0_98:
	s_or_b64 exec, exec, s[8:9]
	s_and_saveexec_b64 s[8:9], vcc
	s_cbranch_execz .LBB0_100
	v_or_b32_e32 v7, 30, v26
	v_mad_i64_i32 v[24:25], s[22:23], v7, s19, v[30:31]
	global_load_dword v23, v[24:25], off nt
.LBB0_100:
	s_or_b64 exec, exec, s[8:9]
	v_mov_b32_e32 v25, 0
	v_mov_b32_e32 v24, 0
	s_and_saveexec_b64 s[8:9], vcc
	s_cbranch_execz .LBB0_102
	v_or_b32_e32 v7, 32, v26
	v_mad_i64_i32 v[28:29], s[22:23], v7, s19, v[30:31]
	global_load_dword v24, v[28:29], off nt
.LBB0_102:
	s_or_b64 exec, exec, s[8:9]
	s_and_saveexec_b64 s[8:9], vcc
	s_cbranch_execz .LBB0_104
	v_or_b32_e32 v7, 34, v26
	v_mad_i64_i32 v[28:29], s[22:23], v7, s19, v[30:31]
	global_load_dword v25, v[28:29], off nt
.LBB0_104:
	s_or_b64 exec, exec, s[8:9]
	v_mov_b32_e32 v29, 0
	v_mov_b32_e32 v28, 0
	s_and_saveexec_b64 s[8:9], vcc
	s_cbranch_execz .LBB0_106
	v_or_b32_e32 v7, 36, v26
	v_mad_i64_i32 v[32:33], s[22:23], v7, s19, v[30:31]
	global_load_dword v28, v[32:33], off nt
.LBB0_106:
	s_or_b64 exec, exec, s[8:9]
	s_and_saveexec_b64 s[8:9], vcc
	s_cbranch_execz .LBB0_108
	v_or_b32_e32 v7, 38, v26
	v_mad_i64_i32 v[32:33], s[22:23], v7, s19, v[30:31]
	global_load_dword v29, v[32:33], off nt
.LBB0_108:
	s_or_b64 exec, exec, s[8:9]
	v_mov_b32_e32 v33, 0
	v_mov_b32_e32 v32, 0
	s_and_saveexec_b64 s[8:9], vcc
	s_cbranch_execz .LBB0_110
	v_or_b32_e32 v7, 40, v26
	v_mad_i64_i32 v[34:35], s[22:23], v7, s19, v[30:31]
	global_load_dword v32, v[34:35], off nt
.LBB0_110:
	s_or_b64 exec, exec, s[8:9]
	s_and_saveexec_b64 s[8:9], vcc
	s_cbranch_execz .LBB0_112
	v_or_b32_e32 v7, 42, v26
	v_mad_i64_i32 v[34:35], s[22:23], v7, s19, v[30:31]
	global_load_dword v33, v[34:35], off nt
.LBB0_112:
	s_or_b64 exec, exec, s[8:9]
	v_mov_b32_e32 v35, 0
	v_mov_b32_e32 v34, 0
	s_and_saveexec_b64 s[8:9], vcc
	s_cbranch_execz .LBB0_114
	v_or_b32_e32 v7, 44, v26
	v_mad_i64_i32 v[36:37], s[22:23], v7, s19, v[30:31]
	global_load_dword v34, v[36:37], off nt
.LBB0_114:
	s_or_b64 exec, exec, s[8:9]
	s_and_saveexec_b64 s[8:9], vcc
	s_cbranch_execz .LBB0_116
	v_or_b32_e32 v7, 46, v26
	v_mad_i64_i32 v[36:37], s[22:23], v7, s19, v[30:31]
	global_load_dword v35, v[36:37], off nt
.LBB0_116:
	s_or_b64 exec, exec, s[8:9]
	v_mov_b32_e32 v37, 0
	v_mov_b32_e32 v36, 0
	s_and_saveexec_b64 s[8:9], vcc
	s_cbranch_execz .LBB0_118
	v_or_b32_e32 v7, 48, v26
	v_mad_i64_i32 v[38:39], s[22:23], v7, s19, v[30:31]
	global_load_dword v36, v[38:39], off nt
.LBB0_118:
	s_or_b64 exec, exec, s[8:9]
	s_and_saveexec_b64 s[8:9], vcc
	s_cbranch_execz .LBB0_120
	v_or_b32_e32 v7, 50, v26
	v_mad_i64_i32 v[38:39], s[22:23], v7, s19, v[30:31]
	global_load_dword v37, v[38:39], off nt
.LBB0_120:
	s_or_b64 exec, exec, s[8:9]
	v_mov_b32_e32 v39, 0
	v_mov_b32_e32 v38, 0
	s_and_saveexec_b64 s[8:9], vcc
	s_cbranch_execz .LBB0_122
	v_or_b32_e32 v7, 52, v26
	s_waitcnt lgkmcnt(0)
	v_mad_i64_i32 v[40:41], s[22:23], v7, s19, v[30:31]
	global_load_dword v38, v[40:41], off nt
.LBB0_122:
	s_or_b64 exec, exec, s[8:9]
	s_and_saveexec_b64 s[8:9], vcc
	s_cbranch_execz .LBB0_124
	v_or_b32_e32 v7, 54, v26
	s_waitcnt lgkmcnt(0)
	v_mad_i64_i32 v[40:41], s[22:23], v7, s19, v[30:31]
	global_load_dword v39, v[40:41], off nt
.LBB0_124:
	s_or_b64 exec, exec, s[8:9]
	s_waitcnt lgkmcnt(0)
	v_mov_b32_e32 v41, 0
	v_mov_b32_e32 v40, 0
	s_and_saveexec_b64 s[8:9], vcc
	s_cbranch_execz .LBB0_126
	v_or_b32_e32 v7, 56, v26
	v_mad_i64_i32 v[42:43], s[22:23], v7, s19, v[30:31]
	global_load_dword v40, v[42:43], off nt
.LBB0_126:
	s_or_b64 exec, exec, s[8:9]
	s_and_saveexec_b64 s[8:9], vcc
	s_cbranch_execz .LBB0_128
	v_or_b32_e32 v7, 58, v26
	v_mad_i64_i32 v[42:43], s[22:23], v7, s19, v[30:31]
	global_load_dword v41, v[42:43], off nt

.LBB0_131:
	v_or_b32_e32 v7, 60, v26
	v_mad_i64_i32 v[56:57], s[22:23], v7, s19, v[30:31]
	global_load_dword v42, v[56:57], off nt
	s_or_b64 exec, exec, s[8:9]
	s_and_saveexec_b64 s[8:9], vcc
	s_cbranch_execz .LBB0_130
.LBB0_132:
	v_or_b32_e32 v7, 62, v26
	v_mad_i64_i32 v[30:31], s[22:23], v7, s19, v[30:31]
	global_load_dword v43, v[30:31], off nt
	s_or_b64 exec, exec, s[8:9]
	s_and_b64 vcc, exec, s[6:7]
	s_cbranch_vccz .LBB0_67
.LBB0_133:
	v_readlane_b32 s52, v238, 5
	v_ashrrev_i32_e32 v27, 31, v26
	v_readlane_b32 s64, v238, 17
	v_readlane_b32 s65, v238, 18
	v_readlane_b32 s53, v238, 6
	v_readlane_b32 s54, v238, 7
	v_lshl_add_u64 v[26:27], v[26:27], 2, s[64:65]
	global_load_dword v30, v[26:27], off nt
	global_load_dword v31, v[26:27], off offset:8
	global_load_dword v56, v[26:27], off offset:16
	global_load_dword v57, v[26:27], off offset:24
	global_load_dword v58, v[26:27], off offset:32
	global_load_dword v59, v[26:27], off offset:40
	global_load_dword v60, v[26:27], off offset:48
	global_load_dword v61, v[26:27], off offset:56
	global_load_dword v62, v[26:27], off offset:64
	global_load_dword v63, v[26:27], off offset:72
	global_load_dword v64, v[26:27], off offset:80
	global_load_dword v65, v[26:27], off offset:88
	global_load_dword v66, v[26:27], off offset:96
	global_load_dword v67, v[26:27], off offset:104
	global_load_dword v68, v[26:27], off offset:112
	global_load_dword v69, v[26:27], off offset:120
	global_load_dword v70, v[26:27], off offset:128
	global_load_dword v71, v[26:27], off offset:136
	global_load_dword v72, v[26:27], off offset:144
	global_load_dword v73, v[26:27], off offset:152
	global_load_dword v74, v[26:27], off offset:160
	global_load_dword v75, v[26:27], off offset:168
	global_load_dword v76, v[26:27], off offset:176
	global_load_dword v77, v[26:27], off offset:184
	global_load_dword v78, v[26:27], off offset:192
	global_load_dword v79, v[26:27], off offset:200
	global_load_dword v80, v[26:27], off offset:208
	global_load_dword v81, v[26:27], off offset:216
	global_load_dword v82, v[26:27], off offset:224
	global_load_dword v83, v[26:27], off offset:232
	global_load_dword v84, v[26:27], off offset:240
	global_load_dword v85, v[26:27], off offset:248
	v_readlane_b32 s55, v238, 8
	v_readlane_b32 s56, v238, 9
	v_readlane_b32 s57, v238, 10
	v_readlane_b32 s58, v238, 11
	v_readlane_b32 s59, v238, 12
	v_readlane_b32 s60, v238, 13
	v_readlane_b32 s61, v238, 14
	v_readlane_b32 s62, v238, 15
	v_readlane_b32 s63, v238, 16
	v_readlane_b32 s66, v238, 19
	v_readlane_b32 s67, v238, 20
	s_waitcnt vmcnt(30)
	v_pk_mul_f32 v[8:9], v[8:9], v[30:31]
	s_waitcnt vmcnt(28)
	v_pk_mul_f32 v[10:11], v[10:11], v[56:57]
	s_waitcnt vmcnt(26)
	v_pk_mul_f32 v[12:13], v[12:13], v[58:59]
	s_waitcnt vmcnt(24)
	v_pk_mul_f32 v[14:15], v[14:15], v[60:61]
	s_waitcnt vmcnt(22)
	v_pk_mul_f32 v[16:17], v[16:17], v[62:63]
	s_waitcnt vmcnt(20)
	v_pk_mul_f32 v[18:19], v[18:19], v[64:65]
	s_waitcnt vmcnt(18)
	v_pk_mul_f32 v[20:21], v[20:21], v[66:67]
	s_waitcnt vmcnt(16)
	v_pk_mul_f32 v[22:23], v[22:23], v[68:69]
	s_waitcnt vmcnt(14)
	v_pk_mul_f32 v[24:25], v[24:25], v[70:71]
	s_waitcnt vmcnt(12)
	v_pk_mul_f32 v[28:29], v[28:29], v[72:73]
	s_waitcnt vmcnt(10)
	v_pk_mul_f32 v[32:33], v[32:33], v[74:75]
	s_waitcnt vmcnt(8)
	v_pk_mul_f32 v[34:35], v[34:35], v[76:77]
	s_waitcnt vmcnt(6)
	v_pk_mul_f32 v[36:37], v[36:37], v[78:79]
	s_waitcnt vmcnt(4)
	v_pk_mul_f32 v[38:39], v[38:39], v[80:81]
	s_waitcnt vmcnt(2)
	v_pk_mul_f32 v[40:41], v[40:41], v[82:83]
	s_waitcnt vmcnt(0)
	v_pk_mul_f32 v[42:43], v[42:43], v[84:85]
	s_branch .LBB0_67

.LBB0_137:
	v_ashrrev_i32_e32 v8, 31, v7
	v_lshrrev_b32_e32 v8, 27, v8
	v_add_u32_e32 v8, v7, v8
	v_ashrrev_i32_e32 v15, 5, v8
	v_lshlrev_b32_e32 v9, 10, v15
	v_sub_u32_e32 v10, v14, v9
	v_readlane_b32 s36, v238, 21
	v_lshlrev_b32_e32 v8, 6, v15
	v_ashrrev_i32_e32 v11, 31, v10
	v_readlane_b32 s38, v238, 23
	v_readlane_b32 s39, v238, 24
	v_or_b32_e32 v12, v8, v1
	v_mov_b32_e32 v9, 0
	v_lshl_add_u64 v[10:11], v[10:11], 2, s[38:39]
	s_and_b64 vcc, exec, s[0:1]
	v_mov_b32_e32 v13, 0
	v_readlane_b32 s37, v238, 22
	v_readlane_b32 s40, v238, 25
	v_readlane_b32 s41, v238, 26
	v_readlane_b32 s42, v238, 27
	v_readlane_b32 s43, v238, 28
	v_readlane_b32 s44, v238, 29
	v_readlane_b32 s45, v238, 30
	v_readlane_b32 s46, v238, 31
	v_readlane_b32 s47, v238, 32
	v_readlane_b32 s48, v238, 33
	v_readlane_b32 s49, v238, 34
	v_readlane_b32 s50, v238, 35
	v_readlane_b32 s51, v238, 36
	s_cbranch_vccnz .LBB0_139
	v_ashrrev_i32_e32 v13, 31, v12
	v_lshlrev_b64 v[16:17], 12, v[12:13]
	v_lshl_add_u64 v[16:17], v[10:11], 0, v[16:17]
	global_load_dword v13, v[16:17], off nt
.LBB0_139:
	s_and_b64 vcc, exec, s[0:1]
	s_cbranch_vccnz .LBB0_141
	v_or_b32_e32 v16, 2, v12
	v_ashrrev_i32_e32 v17, 31, v16
	v_lshlrev_b64 v[16:17], 12, v[16:17]
	v_lshl_add_u64 v[16:17], v[10:11], 0, v[16:17]
	global_load_dword v9, v[16:17], off nt
.LBB0_141:
	v_mov_b32_e32 v16, 0
	s_and_b64 vcc, exec, s[0:1]
	v_mov_b32_e32 v17, 0
	s_cbranch_vccnz .LBB0_143
	v_or_b32_e32 v18, 4, v12
	v_ashrrev_i32_e32 v19, 31, v18
	v_lshlrev_b64 v[18:19], 12, v[18:19]
	v_lshl_add_u64 v[18:19], v[10:11], 0, v[18:19]
	global_load_dword v17, v[18:19], off nt
.LBB0_143:
	s_and_b64 vcc, exec, s[0:1]
	s_cbranch_vccnz .LBB0_145
	v_or_b32_e32 v18, 6, v12
	v_ashrrev_i32_e32 v19, 31, v18
	v_lshlrev_b64 v[18:19], 12, v[18:19]
	v_lshl_add_u64 v[18:19], v[10:11], 0, v[18:19]
	global_load_dword v16, v[18:19], off nt
.LBB0_145:
	v_mov_b32_e32 v18, 0
	s_and_b64 vcc, exec, s[0:1]
	v_mov_b32_e32 v19, 0
	s_cbranch_vccnz .LBB0_147
	v_or_b32_e32 v20, 8, v12
	v_ashrrev_i32_e32 v21, 31, v20
	v_lshlrev_b64 v[20:21], 12, v[20:21]
	v_lshl_add_u64 v[20:21], v[10:11], 0, v[20:21]
	global_load_dword v19, v[20:21], off nt
.LBB0_147:
	s_and_b64 vcc, exec, s[0:1]
	s_cbranch_vccnz .LBB0_149
	v_or_b32_e32 v20, 10, v12
	v_ashrrev_i32_e32 v21, 31, v20
	v_lshlrev_b64 v[20:21], 12, v[20:21]
	v_lshl_add_u64 v[20:21], v[10:11], 0, v[20:21]
	global_load_dword v18, v[20:21], off nt
.LBB0_149:
	v_mov_b32_e32 v20, 0
	s_and_b64 vcc, exec, s[0:1]
	v_mov_b32_e32 v21, 0
	s_cbranch_vccnz .LBB0_151
	v_or_b32_e32 v22, 12, v12
	v_ashrrev_i32_e32 v23, 31, v22
	v_lshlrev_b64 v[22:23], 12, v[22:23]
	v_lshl_add_u64 v[22:23], v[10:11], 0, v[22:23]
	global_load_dword v21, v[22:23], off nt
.LBB0_151:
	s_and_b64 vcc, exec, s[0:1]
	s_cbranch_vccnz .LBB0_153
	v_or_b32_e32 v22, 14, v12
	v_ashrrev_i32_e32 v23, 31, v22
	v_lshlrev_b64 v[22:23], 12, v[22:23]
	v_lshl_add_u64 v[22:23], v[10:11], 0, v[22:23]
	global_load_dword v20, v[22:23], off nt
.LBB0_153:
	v_mov_b32_e32 v22, 0
	s_and_b64 vcc, exec, s[0:1]
	v_mov_b32_e32 v23, 0
	s_cbranch_vccnz .LBB0_155
	v_or_b32_e32 v24, 16, v12
	v_ashrrev_i32_e32 v25, 31, v24
	v_lshlrev_b64 v[24:25], 12, v[24:25]
	v_lshl_add_u64 v[24:25], v[10:11], 0, v[24:25]
	global_load_dword v23, v[24:25], off nt
.LBB0_155:
	s_and_b64 vcc, exec, s[0:1]
	s_cbranch_vccnz .LBB0_157
	v_or_b32_e32 v24, 18, v12
	v_ashrrev_i32_e32 v25, 31, v24
	v_lshlrev_b64 v[24:25], 12, v[24:25]
	v_lshl_add_u64 v[24:25], v[10:11], 0, v[24:25]
	global_load_dword v22, v[24:25], off nt
.LBB0_157:
	v_mov_b32_e32 v24, 0
	s_and_b64 vcc, exec, s[0:1]
	v_mov_b32_e32 v25, 0
	s_cbranch_vccnz .LBB0_159
	v_or_b32_e32 v26, 20, v12
	v_ashrrev_i32_e32 v27, 31, v26
	v_lshlrev_b64 v[26:27], 12, v[26:27]
	v_lshl_add_u64 v[26:27], v[10:11], 0, v[26:27]
	global_load_dword v25, v[26:27], off nt
.LBB0_159:
	s_and_b64 vcc, exec, s[0:1]
	s_cbranch_vccnz .LBB0_161
	v_or_b32_e32 v26, 22, v12
	v_ashrrev_i32_e32 v27, 31, v26
	v_lshlrev_b64 v[26:27], 12, v[26:27]
	v_lshl_add_u64 v[26:27], v[10:11], 0, v[26:27]
	global_load_dword v24, v[26:27], off nt
.LBB0_161:
	v_mov_b32_e32 v26, 0
	s_and_b64 vcc, exec, s[0:1]
	v_mov_b32_e32 v27, 0
	s_cbranch_vccnz .LBB0_163
	v_or_b32_e32 v28, 24, v12
	v_ashrrev_i32_e32 v29, 31, v28
	v_lshlrev_b64 v[28:29], 12, v[28:29]
	v_lshl_add_u64 v[28:29], v[10:11], 0, v[28:29]
	global_load_dword v27, v[28:29], off nt
.LBB0_163:
	s_and_b64 vcc, exec, s[0:1]
	s_cbranch_vccnz .LBB0_165
	v_or_b32_e32 v28, 26, v12
	v_ashrrev_i32_e32 v29, 31, v28
	v_lshlrev_b64 v[28:29], 12, v[28:29]
	v_lshl_add_u64 v[28:29], v[10:11], 0, v[28:29]
	global_load_dword v26, v[28:29], off nt
.LBB0_165:
	v_mov_b32_e32 v28, 0
	s_and_b64 vcc, exec, s[0:1]
	v_mov_b32_e32 v29, 0
	s_cbranch_vccnz .LBB0_167
	v_or_b32_e32 v30, 28, v12
	v_ashrrev_i32_e32 v31, 31, v30
	v_lshlrev_b64 v[30:31], 12, v[30:31]
	v_lshl_add_u64 v[30:31], v[10:11], 0, v[30:31]
	global_load_dword v29, v[30:31], off nt
.LBB0_167:
	s_and_b64 vcc, exec, s[0:1]
	s_cbranch_vccnz .LBB0_169
	v_or_b32_e32 v30, 30, v12
	v_ashrrev_i32_e32 v31, 31, v30
	v_lshlrev_b64 v[30:31], 12, v[30:31]
	v_lshl_add_u64 v[30:31], v[10:11], 0, v[30:31]
	global_load_dword v28, v[30:31], off nt
.LBB0_169:
	v_mov_b32_e32 v30, 0
	s_and_b64 vcc, exec, s[0:1]
	v_mov_b32_e32 v31, 0
	s_cbranch_vccnz .LBB0_171
	v_or_b32_e32 v32, 32, v12
	v_ashrrev_i32_e32 v33, 31, v32
	v_lshlrev_b64 v[32:33], 12, v[32:33]
	v_lshl_add_u64 v[32:33], v[10:11], 0, v[32:33]
	global_load_dword v31, v[32:33], off nt
.LBB0_171:
	s_and_b64 vcc, exec, s[0:1]
	s_cbranch_vccnz .LBB0_173
	v_or_b32_e32 v32, 34, v12
	v_ashrrev_i32_e32 v33, 31, v32
	v_lshlrev_b64 v[32:33], 12, v[32:33]
	v_lshl_add_u64 v[32:33], v[10:11], 0, v[32:33]
	global_load_dword v30, v[32:33], off nt
.LBB0_173:
	v_mov_b32_e32 v32, 0
	s_and_b64 vcc, exec, s[0:1]
	v_mov_b32_e32 v33, 0
	s_cbranch_vccnz .LBB0_175
	v_or_b32_e32 v34, 36, v12
	v_ashrrev_i32_e32 v35, 31, v34
	v_lshlrev_b64 v[34:35], 12, v[34:35]
	v_lshl_add_u64 v[34:35], v[10:11], 0, v[34:35]
	global_load_dword v33, v[34:35], off nt
.LBB0_175:
	s_and_b64 vcc, exec, s[0:1]
	s_cbranch_vccnz .LBB0_177
	v_or_b32_e32 v34, 38, v12
	v_ashrrev_i32_e32 v35, 31, v34
	v_lshlrev_b64 v[34:35], 12, v[34:35]
	v_lshl_add_u64 v[34:35], v[10:11], 0, v[34:35]
	global_load_dword v32, v[34:35], off nt
.LBB0_177:
	v_mov_b32_e32 v34, 0
	s_and_b64 vcc, exec, s[0:1]
	v_mov_b32_e32 v35, 0
	s_cbranch_vccnz .LBB0_179
	v_or_b32_e32 v36, 40, v12
	v_ashrrev_i32_e32 v37, 31, v36
	v_lshlrev_b64 v[36:37], 12, v[36:37]
	v_lshl_add_u64 v[36:37], v[10:11], 0, v[36:37]
	global_load_dword v35, v[36:37], off nt
.LBB0_179:
	s_and_b64 vcc, exec, s[0:1]
	s_cbranch_vccnz .LBB0_181
	v_or_b32_e32 v36, 42, v12
	v_ashrrev_i32_e32 v37, 31, v36
	v_lshlrev_b64 v[36:37], 12, v[36:37]
	v_lshl_add_u64 v[36:37], v[10:11], 0, v[36:37]
	global_load_dword v34, v[36:37], off nt
.LBB0_181:
	v_mov_b32_e32 v36, 0
	s_and_b64 vcc, exec, s[0:1]
	v_mov_b32_e32 v37, 0
	s_cbranch_vccnz .LBB0_183
	v_or_b32_e32 v38, 44, v12
	v_ashrrev_i32_e32 v39, 31, v38
	v_lshlrev_b64 v[38:39], 12, v[38:39]
	v_lshl_add_u64 v[38:39], v[10:11], 0, v[38:39]
	global_load_dword v37, v[38:39], off nt
.LBB0_183:
	s_and_b64 vcc, exec, s[0:1]
	s_cbranch_vccnz .LBB0_185
	v_or_b32_e32 v38, 46, v12
	v_ashrrev_i32_e32 v39, 31, v38
	v_lshlrev_b64 v[38:39], 12, v[38:39]
	v_lshl_add_u64 v[38:39], v[10:11], 0, v[38:39]
	global_load_dword v36, v[38:39], off nt
.LBB0_185:
	v_mov_b32_e32 v38, 0
	s_and_b64 vcc, exec, s[0:1]
	v_mov_b32_e32 v39, 0
	s_cbranch_vccnz .LBB0_187
	v_or_b32_e32 v40, 48, v12
	s_waitcnt lgkmcnt(0)
	v_ashrrev_i32_e32 v41, 31, v40
	v_lshlrev_b64 v[40:41], 12, v[40:41]
	v_lshl_add_u64 v[40:41], v[10:11], 0, v[40:41]
	global_load_dword v39, v[40:41], off nt
.LBB0_187:
	s_and_b64 vcc, exec, s[0:1]
	s_cbranch_vccnz .LBB0_189
	v_or_b32_e32 v40, 50, v12
	s_waitcnt lgkmcnt(0)
	v_ashrrev_i32_e32 v41, 31, v40
	v_lshlrev_b64 v[40:41], 12, v[40:41]
	v_lshl_add_u64 v[40:41], v[10:11], 0, v[40:41]
	global_load_dword v38, v[40:41], off nt
.LBB0_189:
	v_mov_b32_e32 v40, 0
	s_and_b64 vcc, exec, s[0:1]
	s_waitcnt lgkmcnt(0)
	v_mov_b32_e32 v41, 0
	s_cbranch_vccnz .LBB0_191
	v_or_b32_e32 v42, 52, v12
	v_ashrrev_i32_e32 v43, 31, v42
	v_lshlrev_b64 v[42:43], 12, v[42:43]
	v_lshl_add_u64 v[42:43], v[10:11], 0, v[42:43]
	global_load_dword v41, v[42:43], off nt
.LBB0_191:
	s_and_b64 vcc, exec, s[0:1]
	s_cbranch_vccnz .LBB0_193
	v_or_b32_e32 v42, 54, v12
	v_ashrrev_i32_e32 v43, 31, v42
	v_lshlrev_b64 v[42:43], 12, v[42:43]
	v_lshl_add_u64 v[42:43], v[10:11], 0, v[42:43]
	global_load_dword v40, v[42:43], off nt
.LBB0_193:
	v_mov_b32_e32 v42, 0
	s_and_b64 vcc, exec, s[0:1]
	v_mov_b32_e32 v43, 0
	s_cbranch_vccnz .LBB0_195
	v_or_b32_e32 v44, 56, v12
	v_ashrrev_i32_e32 v45, 31, v44
	v_lshlrev_b64 v[44:45], 12, v[44:45]
	v_lshl_add_u64 v[44:45], v[10:11], 0, v[44:45]
	global_load_dword v43, v[44:45], off nt
.LBB0_195:
	s_and_b64 vcc, exec, s[0:1]
	s_cbranch_vccnz .LBB0_197
	v_or_b32_e32 v44, 58, v12
	v_ashrrev_i32_e32 v45, 31, v44
	v_lshlrev_b64 v[44:45], 12, v[44:45]
	v_lshl_add_u64 v[44:45], v[10:11], 0, v[44:45]
	global_load_dword v42, v[44:45], off nt
.LBB0_197:
	v_mov_b32_e32 v44, 0
	s_and_b64 vcc, exec, s[0:1]
	v_mov_b32_e32 v45, 0
	s_cbranch_vccnz .LBB0_199
	v_or_b32_e32 v52, 60, v12
	v_ashrrev_i32_e32 v53, 31, v52
	v_lshlrev_b64 v[52:53], 12, v[52:53]
	v_lshl_add_u64 v[52:53], v[10:11], 0, v[52:53]
	global_load_dword v45, v[52:53], off nt
.LBB0_199:
	s_and_b64 vcc, exec, s[0:1]
	s_cbranch_vccnz .LBB0_136
	v_or_b32_e32 v52, 62, v12
	v_ashrrev_i32_e32 v53, 31, v52
	v_lshlrev_b64 v[52:53], 12, v[52:53]
	v_lshl_add_u64 v[10:11], v[10:11], 0, v[52:53]
	global_load_dword v44, v[10:11], off nt
	s_branch .LBB0_136

.LBB0_206:
	s_andn2_saveexec_b64 s[14:15], s[14:15]
	v_ashrrev_i32_e32 v11, 31, v6
	v_mov_b32_e32 v10, v6
	v_lshl_add_u64 v[28:29], v[10:11], 2, s[12:13]
	s_or_b64 exec, exec, s[14:15]
	v_lshlrev_b32_e32 v8, 6, v8
	v_cmp_ne_u64_e32 vcc, 0, v[28:29]
	v_or_b32_e32 v30, v8, v1
	v_mov_b32_e32 v11, 0
	v_mov_b32_e32 v10, 0
	s_and_saveexec_b64 s[14:15], vcc
	s_cbranch_execz .LBB0_210
	v_mad_i64_i32 v[12:13], s[52:53], v30, s23, v[28:29]
	global_load_dword v10, v[12:13], off nt
.LBB0_210:
	s_or_b64 exec, exec, s[14:15]
	s_and_saveexec_b64 s[14:15], vcc
	s_cbranch_execz .LBB0_212
	v_or_b32_e32 v6, 2, v30
	v_mad_i64_i32 v[12:13], s[52:53], v6, s23, v[28:29]
	global_load_dword v11, v[12:13], off nt
.LBB0_212:
	s_or_b64 exec, exec, s[14:15]
	v_mov_b32_e32 v13, 0
	v_mov_b32_e32 v12, 0
	s_and_saveexec_b64 s[14:15], vcc
	s_cbranch_execz .LBB0_214
	v_or_b32_e32 v6, 4, v30
	v_mad_i64_i32 v[14:15], s[52:53], v6, s23, v[28:29]
	global_load_dword v12, v[14:15], off nt
.LBB0_214:
	s_or_b64 exec, exec, s[14:15]
	s_and_saveexec_b64 s[14:15], vcc
	s_cbranch_execz .LBB0_216
	v_or_b32_e32 v6, 6, v30
	v_mad_i64_i32 v[14:15], s[52:53], v6, s23, v[28:29]
	global_load_dword v13, v[14:15], off nt
.LBB0_216:
	s_or_b64 exec, exec, s[14:15]
	v_mov_b32_e32 v15, 0
	v_mov_b32_e32 v14, 0
	s_and_saveexec_b64 s[14:15], vcc
	s_cbranch_execz .LBB0_218
	v_or_b32_e32 v6, 8, v30
	v_mad_i64_i32 v[16:17], s[52:53], v6, s23, v[28:29]
	global_load_dword v14, v[16:17], off nt
.LBB0_218:
	s_or_b64 exec, exec, s[14:15]
	s_and_saveexec_b64 s[14:15], vcc
	s_cbranch_execz .LBB0_220
	v_or_b32_e32 v6, 10, v30
	v_mad_i64_i32 v[16:17], s[52:53], v6, s23, v[28:29]
	global_load_dword v15, v[16:17], off nt
.LBB0_220:
	s_or_b64 exec, exec, s[14:15]
	v_mov_b32_e32 v17, 0
	v_mov_b32_e32 v16, 0
	s_and_saveexec_b64 s[14:15], vcc
	s_cbranch_execz .LBB0_222
	v_or_b32_e32 v6, 12, v30
	v_mad_i64_i32 v[18:19], s[52:53], v6, s23, v[28:29]
	global_load_dword v16, v[18:19], off nt
.LBB0_222:
	s_or_b64 exec, exec, s[14:15]
	s_and_saveexec_b64 s[14:15], vcc
	s_cbranch_execz .LBB0_224
	v_or_b32_e32 v6, 14, v30
	v_mad_i64_i32 v[18:19], s[52:53], v6, s23, v[28:29]
	global_load_dword v17, v[18:19], off nt
.LBB0_224:
	s_or_b64 exec, exec, s[14:15]
	v_mov_b32_e32 v19, 0
	v_mov_b32_e32 v18, 0
	s_and_saveexec_b64 s[14:15], vcc
	s_cbranch_execz .LBB0_226
	v_or_b32_e32 v6, 16, v30
	v_mad_i64_i32 v[20:21], s[52:53], v6, s23, v[28:29]
	global_load_dword v18, v[20:21], off nt
.LBB0_226:
	s_or_b64 exec, exec, s[14:15]
	s_and_saveexec_b64 s[14:15], vcc
	s_cbranch_execz .LBB0_228
	v_or_b32_e32 v6, 18, v30
	v_mad_i64_i32 v[20:21], s[52:53], v6, s23, v[28:29]
	global_load_dword v19, v[20:21], off nt
.LBB0_228:
	s_or_b64 exec, exec, s[14:15]
	v_mov_b32_e32 v21, 0
	v_mov_b32_e32 v20, 0
	s_and_saveexec_b64 s[14:15], vcc
	s_cbranch_execz .LBB0_230
	v_or_b32_e32 v6, 20, v30
	v_mad_i64_i32 v[22:23], s[52:53], v6, s23, v[28:29]
	global_load_dword v20, v[22:23], off nt
.LBB0_230:
	s_or_b64 exec, exec, s[14:15]
	s_and_saveexec_b64 s[14:15], vcc
	s_cbranch_execz .LBB0_232
	v_or_b32_e32 v6, 22, v30
	v_mad_i64_i32 v[22:23], s[52:53], v6, s23, v[28:29]
	global_load_dword v21, v[22:23], off nt
.LBB0_232:
	s_or_b64 exec, exec, s[14:15]
	v_mov_b32_e32 v23, 0
	v_mov_b32_e32 v22, 0
	s_and_saveexec_b64 s[14:15], vcc
	s_cbranch_execz .LBB0_234
	v_or_b32_e32 v6, 24, v30
	v_mad_i64_i32 v[24:25], s[52:53], v6, s23, v[28:29]
	global_load_dword v22, v[24:25], off nt
.LBB0_234:
	s_or_b64 exec, exec, s[14:15]
	s_and_saveexec_b64 s[14:15], vcc
	s_cbranch_execz .LBB0_236
	v_or_b32_e32 v6, 26, v30
	v_mad_i64_i32 v[24:25], s[52:53], v6, s23, v[28:29]
	global_load_dword v23, v[24:25], off nt
.LBB0_236:
	s_or_b64 exec, exec, s[14:15]
	v_mov_b32_e32 v25, 0
	v_mov_b32_e32 v24, 0
	s_and_saveexec_b64 s[14:15], vcc
	s_cbranch_execz .LBB0_238
	v_or_b32_e32 v6, 28, v30
	v_mad_i64_i32 v[26:27], s[52:53], v6, s23, v[28:29]
	global_load_dword v24, v[26:27], off nt
.LBB0_238:
	s_or_b64 exec, exec, s[14:15]
	s_and_saveexec_b64 s[14:15], vcc
	s_cbranch_execz .LBB0_240
	v_or_b32_e32 v6, 30, v30
	v_mad_i64_i32 v[26:27], s[52:53], v6, s23, v[28:29]
	global_load_dword v25, v[26:27], off nt
.LBB0_240:
	s_or_b64 exec, exec, s[14:15]
	v_mov_b32_e32 v27, 0
	v_mov_b32_e32 v26, 0
	s_and_saveexec_b64 s[14:15], vcc
	s_cbranch_execz .LBB0_242
	v_or_b32_e32 v6, 32, v30
	v_mad_i64_i32 v[32:33], s[52:53], v6, s23, v[28:29]
	global_load_dword v26, v[32:33], off nt
.LBB0_242:
	s_or_b64 exec, exec, s[14:15]
	s_and_saveexec_b64 s[14:15], vcc
	s_cbranch_execz .LBB0_244
	v_or_b32_e32 v6, 34, v30
	v_mad_i64_i32 v[32:33], s[52:53], v6, s23, v[28:29]
	global_load_dword v27, v[32:33], off nt
.LBB0_244:
	s_or_b64 exec, exec, s[14:15]
	v_mov_b32_e32 v33, 0
	v_mov_b32_e32 v32, 0
	s_and_saveexec_b64 s[14:15], vcc
	s_cbranch_execz .LBB0_246
	v_or_b32_e32 v6, 36, v30
	v_mad_i64_i32 v[34:35], s[52:53], v6, s23, v[28:29]
	global_load_dword v32, v[34:35], off nt
.LBB0_246:
	s_or_b64 exec, exec, s[14:15]
	s_and_saveexec_b64 s[14:15], vcc
	s_cbranch_execz .LBB0_248
	v_or_b32_e32 v6, 38, v30
	v_mad_i64_i32 v[34:35], s[52:53], v6, s23, v[28:29]
	global_load_dword v33, v[34:35], off nt
.LBB0_248:
	s_or_b64 exec, exec, s[14:15]
	v_mov_b32_e32 v35, 0
	v_mov_b32_e32 v34, 0
	s_and_saveexec_b64 s[14:15], vcc
	s_cbranch_execz .LBB0_250
	v_or_b32_e32 v6, 40, v30
	v_mad_i64_i32 v[36:37], s[52:53], v6, s23, v[28:29]
	global_load_dword v34, v[36:37], off nt
.LBB0_250:
	s_or_b64 exec, exec, s[14:15]
	s_and_saveexec_b64 s[14:15], vcc
	s_cbranch_execz .LBB0_252
	v_or_b32_e32 v6, 42, v30
	v_mad_i64_i32 v[36:37], s[52:53], v6, s23, v[28:29]
	global_load_dword v35, v[36:37], off nt
.LBB0_252:
	s_or_b64 exec, exec, s[14:15]
	v_mov_b32_e32 v37, 0
	v_mov_b32_e32 v36, 0
	s_and_saveexec_b64 s[14:15], vcc
	s_cbranch_execz .LBB0_254
	v_or_b32_e32 v6, 44, v30
	v_mad_i64_i32 v[38:39], s[52:53], v6, s23, v[28:29]
	global_load_dword v36, v[38:39], off nt
.LBB0_254:
	s_or_b64 exec, exec, s[14:15]
	s_and_saveexec_b64 s[14:15], vcc
	s_cbranch_execz .LBB0_256
	v_or_b32_e32 v6, 46, v30
	v_mad_i64_i32 v[38:39], s[52:53], v6, s23, v[28:29]
	global_load_dword v37, v[38:39], off nt
.LBB0_256:
	s_or_b64 exec, exec, s[14:15]
	v_mov_b32_e32 v39, 0
	v_mov_b32_e32 v38, 0
	s_and_saveexec_b64 s[14:15], vcc
	s_cbranch_execz .LBB0_258
	v_or_b32_e32 v6, 48, v30
	s_waitcnt lgkmcnt(0)
	v_mad_i64_i32 v[40:41], s[52:53], v6, s23, v[28:29]
	global_load_dword v38, v[40:41], off nt
.LBB0_258:
	s_or_b64 exec, exec, s[14:15]
	s_and_saveexec_b64 s[14:15], vcc
	s_cbranch_execz .LBB0_260
	v_or_b32_e32 v6, 50, v30
	s_waitcnt lgkmcnt(0)
	v_mad_i64_i32 v[40:41], s[52:53], v6, s23, v[28:29]
	global_load_dword v39, v[40:41], off nt
.LBB0_260:
	s_or_b64 exec, exec, s[14:15]
	s_waitcnt lgkmcnt(0)
	v_mov_b32_e32 v41, 0
	v_mov_b32_e32 v40, 0
	s_and_saveexec_b64 s[14:15], vcc
	s_cbranch_execz .LBB0_262
	v_or_b32_e32 v6, 52, v30
	v_mad_i64_i32 v[42:43], s[52:53], v6, s23, v[28:29]
	global_load_dword v40, v[42:43], off nt
.LBB0_262:
	s_or_b64 exec, exec, s[14:15]
	s_and_saveexec_b64 s[14:15], vcc
	s_cbranch_execz .LBB0_264
	v_or_b32_e32 v6, 54, v30
	v_mad_i64_i32 v[42:43], s[52:53], v6, s23, v[28:29]
	global_load_dword v41, v[42:43], off nt
.LBB0_264:
	s_or_b64 exec, exec, s[14:15]
	v_mov_b32_e32 v43, 0
	v_mov_b32_e32 v42, 0
	s_and_saveexec_b64 s[14:15], vcc
	s_cbranch_execz .LBB0_266
	v_or_b32_e32 v6, 56, v30
	v_mad_i64_i32 v[44:45], s[52:53], v6, s23, v[28:29]
	global_load_dword v42, v[44:45], off nt
.LBB0_266:
	s_or_b64 exec, exec, s[14:15]
	s_and_saveexec_b64 s[14:15], vcc
	s_cbranch_execz .LBB0_268
	v_or_b32_e32 v6, 58, v30
	v_mad_i64_i32 v[44:45], s[52:53], v6, s23, v[28:29]
	global_load_dword v43, v[44:45], off nt

.LBB0_271:
	v_or_b32_e32 v6, 60, v30
	v_mad_i64_i32 v[54:55], s[52:53], v6, s23, v[28:29]
	global_load_dword v44, v[54:55], off nt
	s_or_b64 exec, exec, s[14:15]
	s_and_saveexec_b64 s[14:15], vcc
	s_cbranch_execz .LBB0_270
.LBB0_272:
	v_or_b32_e32 v6, 62, v30
	v_mad_i64_i32 v[28:29], s[52:53], v6, s23, v[28:29]
	global_load_dword v45, v[28:29], off nt
	s_or_b64 exec, exec, s[14:15]
	s_andn2_b64 vcc, exec, s[6:7]
	s_cbranch_vccnz .LBB0_203
.LBB0_273:
	v_readlane_b32 s36, v238, 21
	v_ashrrev_i32_e32 v31, 31, v30
	v_readlane_b32 s40, v238, 25
	v_readlane_b32 s41, v238, 26
	v_readlane_b32 s37, v238, 22
	v_readlane_b32 s38, v238, 23
	v_lshl_add_u64 v[28:29], v[30:31], 2, s[40:41]
	global_load_dword v30, v[28:29], off nt
	global_load_dword v31, v[28:29], off offset:8
	global_load_dword v54, v[28:29], off offset:16
	global_load_dword v55, v[28:29], off offset:24
	global_load_dword v56, v[28:29], off offset:32
	global_load_dword v57, v[28:29], off offset:40
	global_load_dword v58, v[28:29], off offset:48
	global_load_dword v59, v[28:29], off offset:56
	global_load_dword v60, v[28:29], off offset:64
	global_load_dword v61, v[28:29], off offset:72
	global_load_dword v62, v[28:29], off offset:80
	global_load_dword v63, v[28:29], off offset:88
	global_load_dword v64, v[28:29], off offset:96
	global_load_dword v65, v[28:29], off offset:104
	global_load_dword v66, v[28:29], off offset:112
	global_load_dword v67, v[28:29], off offset:120
	global_load_dword v68, v[28:29], off offset:128
	global_load_dword v69, v[28:29], off offset:136
	global_load_dword v70, v[28:29], off offset:144
	global_load_dword v71, v[28:29], off offset:152
	global_load_dword v72, v[28:29], off offset:160
	global_load_dword v73, v[28:29], off offset:168
	global_load_dword v74, v[28:29], off offset:176
	global_load_dword v75, v[28:29], off offset:184
	global_load_dword v76, v[28:29], off offset:192
	global_load_dword v77, v[28:29], off offset:200
	global_load_dword v78, v[28:29], off offset:208
	global_load_dword v79, v[28:29], off offset:216
	global_load_dword v80, v[28:29], off offset:224
	global_load_dword v81, v[28:29], off offset:232
	global_load_dword v82, v[28:29], off offset:240
	global_load_dword v83, v[28:29], off offset:248
	v_readlane_b32 s39, v238, 24
	v_readlane_b32 s42, v238, 27
	v_readlane_b32 s43, v238, 28
	v_readlane_b32 s44, v238, 29
	v_readlane_b32 s45, v238, 30
	v_readlane_b32 s46, v238, 31
	v_readlane_b32 s47, v238, 32
	v_readlane_b32 s48, v238, 33
	v_readlane_b32 s49, v238, 34
	v_readlane_b32 s50, v238, 35
	v_readlane_b32 s51, v238, 36
	s_waitcnt vmcnt(30)
	v_pk_mul_f32 v[10:11], v[10:11], v[30:31]
	s_waitcnt vmcnt(28)
	v_pk_mul_f32 v[12:13], v[12:13], v[54:55]
	s_waitcnt vmcnt(26)
	v_pk_mul_f32 v[14:15], v[14:15], v[56:57]
	s_waitcnt vmcnt(24)
	v_pk_mul_f32 v[16:17], v[16:17], v[58:59]
	s_waitcnt vmcnt(22)
	v_pk_mul_f32 v[18:19], v[18:19], v[60:61]
	s_waitcnt vmcnt(20)
	v_pk_mul_f32 v[20:21], v[20:21], v[62:63]
	s_waitcnt vmcnt(18)
	v_pk_mul_f32 v[22:23], v[22:23], v[64:65]
	s_waitcnt vmcnt(16)
	v_pk_mul_f32 v[24:25], v[24:25], v[66:67]
	s_waitcnt vmcnt(14)
	v_pk_mul_f32 v[26:27], v[26:27], v[68:69]
	s_waitcnt vmcnt(12)
	v_pk_mul_f32 v[32:33], v[32:33], v[70:71]
	s_waitcnt vmcnt(10)
	v_pk_mul_f32 v[34:35], v[34:35], v[72:73]
	s_waitcnt vmcnt(8)
	v_pk_mul_f32 v[36:37], v[36:37], v[74:75]
	s_waitcnt vmcnt(6)
	v_pk_mul_f32 v[38:39], v[38:39], v[76:77]
	s_waitcnt vmcnt(4)
	v_pk_mul_f32 v[40:41], v[40:41], v[78:79]
	s_waitcnt vmcnt(2)
	v_pk_mul_f32 v[42:43], v[42:43], v[80:81]
	s_waitcnt vmcnt(0)
	v_pk_mul_f32 v[44:45], v[44:45], v[82:83]
	s_branch .LBB0_203

.LBB0_283:
	v_ashrrev_i32_e32 v6, 31, v52
	v_lshrrev_b32_e32 v6, 25, v6
	v_add_u32_e32 v6, v52, v6
	v_ashrrev_i32_e32 v6, 7, v6
	v_lshlrev_b32_e32 v9, 12, v6
	v_lshlrev_b32_e32 v8, 6, v6
	v_sub_u32_e32 v6, v53, v9
	v_add_u32_e32 v10, v6, v48
	v_lshrrev_b32_e32 v6, 1, v6
	v_and_b32_e32 v11, 0x7f, v10
	v_and_or_b32 v6, v6, s18, v11
	v_and_b32_e32 v11, 4, v52
	v_cmp_eq_u32_e32 vcc, 0, v11
	v_add_u32_e32 v12, 0x1c10, v6
	v_readlane_b32 s36, v238, 21
	v_cndmask_b32_e32 v11, v54, v55, vcc
	v_or_b32_e32 v11, v6, v11
	v_cndmask_b32_e32 v6, v12, v6, vcc
	v_cmp_gt_i32_e32 vcc, s14, v10
	v_readlane_b32 s42, v238, 27
	v_readlane_b32 s43, v238, 28
	v_cndmask_b32_e32 v6, v6, v11, vcc
	v_lshlrev_b32_e32 v6, 2, v6
	s_waitcnt lgkmcnt(0)
	v_lshl_add_u64 v[40:41], s[42:43], 0, v[6:7]
	v_or_b32_e32 v34, v8, v1
	s_and_b64 vcc, exec, s[0:1]
	v_mov_b32_e32 v10, 0
	v_readlane_b32 s37, v238, 22
	v_readlane_b32 s38, v238, 23
	v_readlane_b32 s39, v238, 24
	v_readlane_b32 s40, v238, 25
	v_readlane_b32 s41, v238, 26
	v_readlane_b32 s44, v238, 29
	v_readlane_b32 s45, v238, 30
	v_readlane_b32 s46, v238, 31
	v_readlane_b32 s47, v238, 32
	v_readlane_b32 s48, v238, 33
	v_readlane_b32 s49, v238, 34
	v_readlane_b32 s50, v238, 35
	v_readlane_b32 s51, v238, 36
	s_cbranch_vccnz .LBB0_285
	v_mad_i64_i32 v[10:11], s[22:23], v34, s19, v[40:41]
	global_load_dword v10, v[10:11], off nt
.LBB0_285:
	v_mov_b32_e32 v12, 0
	s_and_b64 vcc, exec, s[0:1]
	v_mov_b32_e32 v11, 0
	s_cbranch_vccnz .LBB0_287
	v_or_b32_e32 v6, 2, v34
	v_mad_i64_i32 v[14:15], s[22:23], v6, s19, v[40:41]
	global_load_dword v11, v[14:15], off nt
.LBB0_287:
	s_and_b64 vcc, exec, s[0:1]
	s_cbranch_vccnz .LBB0_289
	v_or_b32_e32 v6, 4, v34
	v_mad_i64_i32 v[12:13], s[22:23], v6, s19, v[40:41]
	global_load_dword v12, v[12:13], off nt
.LBB0_289:
	v_mov_b32_e32 v14, 0
	s_and_b64 vcc, exec, s[0:1]
	v_mov_b32_e32 v13, 0
	s_cbranch_vccnz .LBB0_291
	v_or_b32_e32 v6, 6, v34
	v_mad_i64_i32 v[16:17], s[22:23], v6, s19, v[40:41]
	global_load_dword v13, v[16:17], off nt
.LBB0_291:
	s_and_b64 vcc, exec, s[0:1]
	s_cbranch_vccnz .LBB0_293
	v_or_b32_e32 v6, 8, v34
	v_mad_i64_i32 v[14:15], s[22:23], v6, s19, v[40:41]
	global_load_dword v14, v[14:15], off nt
.LBB0_293:
	v_mov_b32_e32 v16, 0
	s_and_b64 vcc, exec, s[0:1]
	v_mov_b32_e32 v15, 0
	s_cbranch_vccnz .LBB0_295
	v_or_b32_e32 v6, 10, v34
	v_mad_i64_i32 v[18:19], s[22:23], v6, s19, v[40:41]
	global_load_dword v15, v[18:19], off nt
.LBB0_295:
	s_and_b64 vcc, exec, s[0:1]
	s_cbranch_vccnz .LBB0_297
	v_or_b32_e32 v6, 12, v34
	v_mad_i64_i32 v[16:17], s[22:23], v6, s19, v[40:41]
	global_load_dword v16, v[16:17], off nt
.LBB0_297:
	v_mov_b32_e32 v18, 0
	s_and_b64 vcc, exec, s[0:1]
	v_mov_b32_e32 v17, 0
	s_cbranch_vccnz .LBB0_299
	v_or_b32_e32 v6, 14, v34
	v_mad_i64_i32 v[20:21], s[22:23], v6, s19, v[40:41]
	global_load_dword v17, v[20:21], off nt
.LBB0_299:
	s_and_b64 vcc, exec, s[0:1]
	s_cbranch_vccnz .LBB0_301
	v_or_b32_e32 v6, 16, v34
	v_mad_i64_i32 v[18:19], s[22:23], v6, s19, v[40:41]
	global_load_dword v18, v[18:19], off nt
.LBB0_301:
	v_mov_b32_e32 v20, 0
	s_and_b64 vcc, exec, s[0:1]
	v_mov_b32_e32 v19, 0
	s_cbranch_vccnz .LBB0_303
	v_or_b32_e32 v6, 18, v34
	v_mad_i64_i32 v[22:23], s[22:23], v6, s19, v[40:41]
	global_load_dword v19, v[22:23], off nt
.LBB0_303:
	s_and_b64 vcc, exec, s[0:1]
	s_cbranch_vccnz .LBB0_305
	v_or_b32_e32 v6, 20, v34
	v_mad_i64_i32 v[20:21], s[22:23], v6, s19, v[40:41]
	global_load_dword v20, v[20:21], off nt
.LBB0_305:
	v_mov_b32_e32 v22, 0
	s_and_b64 vcc, exec, s[0:1]
	v_mov_b32_e32 v21, 0
	s_cbranch_vccnz .LBB0_307
	v_or_b32_e32 v6, 22, v34
	v_mad_i64_i32 v[24:25], s[22:23], v6, s19, v[40:41]
	global_load_dword v21, v[24:25], off nt
.LBB0_307:
	s_and_b64 vcc, exec, s[0:1]
	s_cbranch_vccnz .LBB0_309
	v_or_b32_e32 v6, 24, v34
	v_mad_i64_i32 v[22:23], s[22:23], v6, s19, v[40:41]
	global_load_dword v22, v[22:23], off nt
.LBB0_309:
	v_mov_b32_e32 v24, 0
	s_and_b64 vcc, exec, s[0:1]
	v_mov_b32_e32 v23, 0
	s_cbranch_vccnz .LBB0_311
	v_or_b32_e32 v6, 26, v34
	v_mad_i64_i32 v[26:27], s[22:23], v6, s19, v[40:41]
	global_load_dword v23, v[26:27], off nt
.LBB0_311:
	s_and_b64 vcc, exec, s[0:1]
	s_cbranch_vccnz .LBB0_313
	v_or_b32_e32 v6, 28, v34
	v_mad_i64_i32 v[24:25], s[22:23], v6, s19, v[40:41]
	global_load_dword v24, v[24:25], off nt
.LBB0_313:
	v_mov_b32_e32 v26, 0
	s_and_b64 vcc, exec, s[0:1]
	v_mov_b32_e32 v25, 0
	s_cbranch_vccnz .LBB0_315
	v_or_b32_e32 v6, 30, v34
	v_mad_i64_i32 v[28:29], s[22:23], v6, s19, v[40:41]
	global_load_dword v25, v[28:29], off nt
.LBB0_315:
	s_and_b64 vcc, exec, s[0:1]
	s_cbranch_vccnz .LBB0_317
	v_or_b32_e32 v6, 32, v34
	v_mad_i64_i32 v[26:27], s[22:23], v6, s19, v[40:41]
	global_load_dword v26, v[26:27], off nt
.LBB0_317:
	v_mov_b32_e32 v28, 0
	s_and_b64 vcc, exec, s[0:1]
	v_mov_b32_e32 v27, 0
	s_cbranch_vccnz .LBB0_319
	v_or_b32_e32 v6, 34, v34
	v_mad_i64_i32 v[30:31], s[22:23], v6, s19, v[40:41]
	global_load_dword v27, v[30:31], off nt
.LBB0_319:
	s_and_b64 vcc, exec, s[0:1]
	s_cbranch_vccnz .LBB0_321
	v_or_b32_e32 v6, 36, v34
	v_mad_i64_i32 v[28:29], s[22:23], v6, s19, v[40:41]
	global_load_dword v28, v[28:29], off nt
.LBB0_321:
	v_mov_b32_e32 v30, 0
	s_and_b64 vcc, exec, s[0:1]
	v_mov_b32_e32 v29, 0
	s_cbranch_vccnz .LBB0_323
	v_or_b32_e32 v6, 38, v34
	v_mad_i64_i32 v[32:33], s[22:23], v6, s19, v[40:41]
	global_load_dword v29, v[32:33], off nt
.LBB0_323:
	s_and_b64 vcc, exec, s[0:1]
	s_cbranch_vccnz .LBB0_325
	v_or_b32_e32 v6, 40, v34
	v_mad_i64_i32 v[30:31], s[22:23], v6, s19, v[40:41]
	global_load_dword v30, v[30:31], off nt
.LBB0_325:
	v_mov_b32_e32 v32, 0
	s_and_b64 vcc, exec, s[0:1]
	v_mov_b32_e32 v31, 0
	s_cbranch_vccnz .LBB0_327
	v_or_b32_e32 v6, 42, v34
	v_mad_i64_i32 v[36:37], s[22:23], v6, s19, v[40:41]
	global_load_dword v31, v[36:37], off nt
.LBB0_327:
	s_and_b64 vcc, exec, s[0:1]
	s_cbranch_vccnz .LBB0_329
	v_or_b32_e32 v6, 44, v34
	v_mad_i64_i32 v[32:33], s[22:23], v6, s19, v[40:41]
	global_load_dword v32, v[32:33], off nt
.LBB0_329:
	v_mov_b32_e32 v36, 0
	s_and_b64 vcc, exec, s[0:1]
	v_mov_b32_e32 v33, 0
	s_cbranch_vccnz .LBB0_331
	v_or_b32_e32 v6, 46, v34
	v_mad_i64_i32 v[38:39], s[22:23], v6, s19, v[40:41]
	global_load_dword v33, v[38:39], off nt
.LBB0_331:
	s_and_b64 vcc, exec, s[0:1]
	s_cbranch_vccnz .LBB0_333
	v_or_b32_e32 v6, 48, v34
	v_mad_i64_i32 v[36:37], s[22:23], v6, s19, v[40:41]
	global_load_dword v36, v[36:37], off nt
.LBB0_333:
	v_mov_b32_e32 v38, 0
	s_and_b64 vcc, exec, s[0:1]
	v_mov_b32_e32 v37, 0
	s_cbranch_vccnz .LBB0_335
	v_or_b32_e32 v6, 50, v34
	v_mad_i64_i32 v[42:43], s[22:23], v6, s19, v[40:41]
	global_load_dword v37, v[42:43], off nt
.LBB0_335:
	s_and_b64 vcc, exec, s[0:1]
	s_cbranch_vccnz .LBB0_337
	v_or_b32_e32 v6, 52, v34
	v_mad_i64_i32 v[38:39], s[22:23], v6, s19, v[40:41]
	global_load_dword v38, v[38:39], off nt
.LBB0_337:
	v_mov_b32_e32 v42, 0
	s_and_b64 vcc, exec, s[0:1]
	v_mov_b32_e32 v39, 0
	s_cbranch_vccnz .LBB0_339
	v_or_b32_e32 v6, 54, v34
	v_mad_i64_i32 v[44:45], s[22:23], v6, s19, v[40:41]
	global_load_dword v39, v[44:45], off nt
.LBB0_339:
	s_and_b64 vcc, exec, s[0:1]
	s_cbranch_vccnz .LBB0_341
	v_or_b32_e32 v6, 56, v34
	v_mad_i64_i32 v[42:43], s[22:23], v6, s19, v[40:41]
	global_load_dword v42, v[42:43], off nt
.LBB0_341:
	v_mov_b32_e32 v44, 0
	s_and_b64 vcc, exec, s[0:1]
	v_mov_b32_e32 v43, 0
	s_cbranch_vccnz .LBB0_343
	v_or_b32_e32 v6, 58, v34
	v_mad_i64_i32 v[56:57], s[22:23], v6, s19, v[40:41]
	global_load_dword v43, v[56:57], off nt
.LBB0_343:
	s_and_b64 vcc, exec, s[0:1]
	s_cbranch_vccnz .LBB0_345
	v_or_b32_e32 v6, 60, v34
	v_mad_i64_i32 v[44:45], s[22:23], v6, s19, v[40:41]
	global_load_dword v44, v[44:45], off nt
.LBB0_345:
	s_and_b64 vcc, exec, s[0:1]
	s_cbranch_vccnz .LBB0_347
	v_or_b32_e32 v6, 62, v34
	v_mad_i64_i32 v[40:41], s[22:23], v6, s19, v[40:41]
	global_load_dword v45, v[40:41], off nt
	s_andn2_b64 vcc, exec, s[12:13]
	s_cbranch_vccz .LBB0_348
	s_branch .LBB0_282

.LBB0_348:
	v_readlane_b32 s36, v238, 21
	v_ashrrev_i32_e32 v35, 31, v34
	v_readlane_b32 s40, v238, 25
	v_readlane_b32 s41, v238, 26
	v_readlane_b32 s37, v238, 22
	v_readlane_b32 s38, v238, 23
	v_lshl_add_u64 v[34:35], v[34:35], 2, s[40:41]
	global_load_dword v40, v[34:35], off nt
	global_load_dword v41, v[34:35], off offset:8
	global_load_dword v56, v[34:35], off offset:16
	global_load_dword v57, v[34:35], off offset:24
	global_load_dword v58, v[34:35], off offset:32
	global_load_dword v59, v[34:35], off offset:40
	global_load_dword v60, v[34:35], off offset:48
	global_load_dword v61, v[34:35], off offset:56
	global_load_dword v62, v[34:35], off offset:64
	global_load_dword v63, v[34:35], off offset:72
	global_load_dword v64, v[34:35], off offset:80
	global_load_dword v65, v[34:35], off offset:88
	global_load_dword v66, v[34:35], off offset:96
	global_load_dword v67, v[34:35], off offset:104
	global_load_dword v68, v[34:35], off offset:112
	global_load_dword v69, v[34:35], off offset:120
	global_load_dword v70, v[34:35], off offset:128
	global_load_dword v71, v[34:35], off offset:136
	global_load_dword v72, v[34:35], off offset:144
	global_load_dword v73, v[34:35], off offset:152
	global_load_dword v74, v[34:35], off offset:160
	global_load_dword v75, v[34:35], off offset:168
	global_load_dword v76, v[34:35], off offset:176
	global_load_dword v77, v[34:35], off offset:184
	global_load_dword v78, v[34:35], off offset:192
	global_load_dword v79, v[34:35], off offset:200
	global_load_dword v80, v[34:35], off offset:208
	global_load_dword v81, v[34:35], off offset:216
	global_load_dword v82, v[34:35], off offset:224
	global_load_dword v83, v[34:35], off offset:232
	global_load_dword v84, v[34:35], off offset:240
	global_load_dword v85, v[34:35], off offset:248
	v_readlane_b32 s39, v238, 24
	v_readlane_b32 s42, v238, 27
	v_readlane_b32 s43, v238, 28
	v_readlane_b32 s44, v238, 29
	v_readlane_b32 s45, v238, 30
	v_readlane_b32 s46, v238, 31
	v_readlane_b32 s47, v238, 32
	v_readlane_b32 s48, v238, 33
	v_readlane_b32 s49, v238, 34
	v_readlane_b32 s50, v238, 35
	v_readlane_b32 s51, v238, 36
	s_waitcnt vmcnt(30)
	v_pk_mul_f32 v[10:11], v[10:11], v[40:41]
	s_waitcnt vmcnt(28)
	v_pk_mul_f32 v[12:13], v[12:13], v[56:57]
	s_waitcnt vmcnt(26)
	v_pk_mul_f32 v[14:15], v[14:15], v[58:59]
	s_waitcnt vmcnt(24)
	v_pk_mul_f32 v[16:17], v[16:17], v[60:61]
	s_waitcnt vmcnt(22)
	v_pk_mul_f32 v[18:19], v[18:19], v[62:63]
	s_waitcnt vmcnt(20)
	v_pk_mul_f32 v[20:21], v[20:21], v[64:65]
	s_waitcnt vmcnt(18)
	v_pk_mul_f32 v[22:23], v[22:23], v[66:67]
	s_waitcnt vmcnt(16)
	v_pk_mul_f32 v[24:25], v[24:25], v[68:69]
	s_waitcnt vmcnt(14)
	v_pk_mul_f32 v[26:27], v[26:27], v[70:71]
	s_waitcnt vmcnt(12)
	v_pk_mul_f32 v[28:29], v[28:29], v[72:73]
	s_waitcnt vmcnt(10)
	v_pk_mul_f32 v[30:31], v[30:31], v[74:75]
	s_waitcnt vmcnt(8)
	v_pk_mul_f32 v[32:33], v[32:33], v[76:77]
	s_waitcnt vmcnt(6)
	v_pk_mul_f32 v[36:37], v[36:37], v[78:79]
	s_waitcnt vmcnt(4)
	v_pk_mul_f32 v[38:39], v[38:39], v[80:81]
	s_waitcnt vmcnt(2)
	v_pk_mul_f32 v[42:43], v[42:43], v[82:83]
	s_waitcnt vmcnt(0)
	v_pk_mul_f32 v[44:45], v[44:45], v[84:85]
	s_branch .LBB0_282

.LBB0_353:
	v_ashrrev_i32_e32 v6, 31, v44
	v_lshrrev_b32_e32 v6, 26, v6
	v_add_u32_e32 v6, v44, v6
	v_ashrrev_i32_e32 v8, 6, v6
	v_lshlrev_b32_e32 v7, 11, v8
	v_lshlrev_b32_e32 v8, 10, v8
	v_sub_u32_e32 v9, v45, v7
	v_sub_u32_e32 v8, v51, v8
	v_and_b32_e32 v8, 0xffffff80, v8
	v_and_b32_e32 v9, 0x60, v9
	v_or3_b32 v8, v9, v8, v48
	v_and_b32_e32 v9, 4, v44
	v_cmp_eq_u32_e32 vcc, 0, v9
	v_readlane_b32 s36, v238, 21
	v_and_b32_e32 v6, 0xffffffc0, v6
	v_cndmask_b32_e32 v9, v52, v53, vcc
	v_add_u32_e32 v8, v8, v9
	v_ashrrev_i32_e32 v9, 31, v8
	v_readlane_b32 s42, v238, 27
	v_readlane_b32 s43, v238, 28
	v_or_b32_e32 v32, v6, v1
	s_and_b64 vcc, exec, s[4:5]
	v_lshl_add_u64 v[36:37], v[8:9], 2, s[42:43]
	v_mov_b32_e32 v9, 0
	v_mov_b32_e32 v8, 0
	v_readlane_b32 s37, v238, 22
	v_readlane_b32 s38, v238, 23
	v_readlane_b32 s39, v238, 24
	v_readlane_b32 s40, v238, 25
	v_readlane_b32 s41, v238, 26
	v_readlane_b32 s44, v238, 29
	v_readlane_b32 s45, v238, 30
	v_readlane_b32 s46, v238, 31
	v_readlane_b32 s47, v238, 32
	v_readlane_b32 s48, v238, 33
	v_readlane_b32 s49, v238, 34
	v_readlane_b32 s50, v238, 35
	v_readlane_b32 s51, v238, 36
	s_cbranch_vccnz .LBB0_355
	v_mad_i64_i32 v[10:11], s[22:23], v32, s19, v[36:37]
	global_load_dword v8, v[10:11], off nt
.LBB0_355:
	s_and_b64 vcc, exec, s[4:5]
	s_cbranch_vccnz .LBB0_357
	v_or_b32_e32 v9, 2, v32
	v_mad_i64_i32 v[10:11], s[22:23], v9, s19, v[36:37]
	global_load_dword v9, v[10:11], off nt
.LBB0_357:
	v_mov_b32_e32 v11, 0
	s_and_b64 vcc, exec, s[4:5]
	v_mov_b32_e32 v10, 0
	s_cbranch_vccnz .LBB0_359
	v_or_b32_e32 v10, 4, v32
	v_mad_i64_i32 v[12:13], s[22:23], v10, s19, v[36:37]
	global_load_dword v10, v[12:13], off nt
.LBB0_359:
	s_and_b64 vcc, exec, s[4:5]
	s_cbranch_vccnz .LBB0_361
	v_or_b32_e32 v11, 6, v32
	v_mad_i64_i32 v[12:13], s[22:23], v11, s19, v[36:37]
	global_load_dword v11, v[12:13], off nt
.LBB0_361:
	v_mov_b32_e32 v13, 0
	s_and_b64 vcc, exec, s[4:5]
	v_mov_b32_e32 v12, 0
	s_cbranch_vccnz .LBB0_363
	v_or_b32_e32 v12, 8, v32
	v_mad_i64_i32 v[14:15], s[22:23], v12, s19, v[36:37]
	global_load_dword v12, v[14:15], off nt
.LBB0_363:
	s_and_b64 vcc, exec, s[4:5]
	s_cbranch_vccnz .LBB0_365
	v_or_b32_e32 v13, 10, v32
	v_mad_i64_i32 v[14:15], s[22:23], v13, s19, v[36:37]
	global_load_dword v13, v[14:15], off nt
.LBB0_365:
	v_mov_b32_e32 v15, 0
	s_and_b64 vcc, exec, s[4:5]
	v_mov_b32_e32 v14, 0
	s_cbranch_vccnz .LBB0_367
	v_or_b32_e32 v14, 12, v32
	v_mad_i64_i32 v[16:17], s[22:23], v14, s19, v[36:37]
	global_load_dword v14, v[16:17], off nt
.LBB0_367:
	s_and_b64 vcc, exec, s[4:5]
	s_cbranch_vccnz .LBB0_369
	v_or_b32_e32 v15, 14, v32
	v_mad_i64_i32 v[16:17], s[22:23], v15, s19, v[36:37]
	global_load_dword v15, v[16:17], off nt
.LBB0_369:
	v_mov_b32_e32 v17, 0
	s_and_b64 vcc, exec, s[4:5]
	v_mov_b32_e32 v16, 0
	s_cbranch_vccnz .LBB0_371
	v_or_b32_e32 v16, 16, v32
	v_mad_i64_i32 v[18:19], s[22:23], v16, s19, v[36:37]
	global_load_dword v16, v[18:19], off nt
.LBB0_371:
	s_and_b64 vcc, exec, s[4:5]
	s_cbranch_vccnz .LBB0_373
	v_or_b32_e32 v17, 18, v32
	v_mad_i64_i32 v[18:19], s[22:23], v17, s19, v[36:37]
	global_load_dword v17, v[18:19], off nt
.LBB0_373:
	v_mov_b32_e32 v19, 0
	s_and_b64 vcc, exec, s[4:5]
	v_mov_b32_e32 v18, 0
	s_cbranch_vccnz .LBB0_375
	v_or_b32_e32 v18, 20, v32
	v_mad_i64_i32 v[20:21], s[22:23], v18, s19, v[36:37]
	global_load_dword v18, v[20:21], off nt
.LBB0_375:
	s_and_b64 vcc, exec, s[4:5]
	s_cbranch_vccnz .LBB0_377
	v_or_b32_e32 v19, 22, v32
	v_mad_i64_i32 v[20:21], s[22:23], v19, s19, v[36:37]
	global_load_dword v19, v[20:21], off nt
.LBB0_377:
	v_mov_b32_e32 v21, 0
	s_and_b64 vcc, exec, s[4:5]
	v_mov_b32_e32 v20, 0
	s_cbranch_vccnz .LBB0_379
	v_or_b32_e32 v20, 24, v32
	v_mad_i64_i32 v[22:23], s[22:23], v20, s19, v[36:37]
	global_load_dword v20, v[22:23], off nt
.LBB0_379:
	s_and_b64 vcc, exec, s[4:5]
	s_cbranch_vccnz .LBB0_381
	v_or_b32_e32 v21, 26, v32
	v_mad_i64_i32 v[22:23], s[22:23], v21, s19, v[36:37]
	global_load_dword v21, v[22:23], off nt
.LBB0_381:
	v_mov_b32_e32 v23, 0
	s_and_b64 vcc, exec, s[4:5]
	v_mov_b32_e32 v22, 0
	s_cbranch_vccnz .LBB0_383
	v_or_b32_e32 v22, 28, v32
	v_mad_i64_i32 v[24:25], s[22:23], v22, s19, v[36:37]
	global_load_dword v22, v[24:25], off nt
.LBB0_383:
	s_and_b64 vcc, exec, s[4:5]
	s_cbranch_vccnz .LBB0_385
	v_or_b32_e32 v23, 30, v32
	v_mad_i64_i32 v[24:25], s[22:23], v23, s19, v[36:37]
	global_load_dword v23, v[24:25], off nt
.LBB0_385:
	v_mov_b32_e32 v25, 0
	s_and_b64 vcc, exec, s[4:5]
	v_mov_b32_e32 v24, 0
	s_cbranch_vccnz .LBB0_387
	v_or_b32_e32 v24, 32, v32
	v_mad_i64_i32 v[26:27], s[22:23], v24, s19, v[36:37]
	global_load_dword v24, v[26:27], off nt
.LBB0_387:
	s_and_b64 vcc, exec, s[4:5]
	s_cbranch_vccnz .LBB0_389
	v_or_b32_e32 v25, 34, v32
	v_mad_i64_i32 v[26:27], s[22:23], v25, s19, v[36:37]
	global_load_dword v25, v[26:27], off nt
.LBB0_389:
	v_mov_b32_e32 v27, 0
	s_and_b64 vcc, exec, s[4:5]
	v_mov_b32_e32 v26, 0
	s_cbranch_vccnz .LBB0_391
	v_or_b32_e32 v26, 36, v32
	v_mad_i64_i32 v[28:29], s[22:23], v26, s19, v[36:37]
	global_load_dword v26, v[28:29], off nt
.LBB0_391:
	s_and_b64 vcc, exec, s[4:5]
	s_cbranch_vccnz .LBB0_393
	v_or_b32_e32 v27, 38, v32
	v_mad_i64_i32 v[28:29], s[22:23], v27, s19, v[36:37]
	global_load_dword v27, v[28:29], off nt
.LBB0_393:
	v_mov_b32_e32 v29, 0
	s_and_b64 vcc, exec, s[4:5]
	v_mov_b32_e32 v28, 0
	s_cbranch_vccnz .LBB0_395
	v_or_b32_e32 v28, 40, v32
	v_mad_i64_i32 v[30:31], s[22:23], v28, s19, v[36:37]
	global_load_dword v28, v[30:31], off nt
.LBB0_395:
	s_and_b64 vcc, exec, s[4:5]
	s_cbranch_vccnz .LBB0_397
	v_or_b32_e32 v29, 42, v32
	v_mad_i64_i32 v[30:31], s[22:23], v29, s19, v[36:37]
	global_load_dword v29, v[30:31], off nt
.LBB0_397:
	v_mov_b32_e32 v31, 0
	s_and_b64 vcc, exec, s[4:5]
	v_mov_b32_e32 v30, 0
	s_cbranch_vccnz .LBB0_399
	v_or_b32_e32 v30, 44, v32
	v_mad_i64_i32 v[34:35], s[22:23], v30, s19, v[36:37]
	global_load_dword v30, v[34:35], off nt
.LBB0_399:
	s_and_b64 vcc, exec, s[4:5]
	s_cbranch_vccnz .LBB0_401
	v_or_b32_e32 v31, 46, v32
	v_mad_i64_i32 v[34:35], s[22:23], v31, s19, v[36:37]
	global_load_dword v31, v[34:35], off nt
.LBB0_401:
	v_mov_b32_e32 v35, 0
	s_and_b64 vcc, exec, s[4:5]
	v_mov_b32_e32 v34, 0
	s_cbranch_vccnz .LBB0_403
	v_or_b32_e32 v33, 48, v32
	v_mad_i64_i32 v[38:39], s[22:23], v33, s19, v[36:37]
	global_load_dword v34, v[38:39], off nt
.LBB0_403:
	s_and_b64 vcc, exec, s[4:5]
	s_cbranch_vccnz .LBB0_405
	v_or_b32_e32 v33, 50, v32
	v_mad_i64_i32 v[38:39], s[22:23], v33, s19, v[36:37]
	global_load_dword v35, v[38:39], off nt
.LBB0_405:
	v_mov_b32_e32 v39, 0
	s_and_b64 vcc, exec, s[4:5]
	v_mov_b32_e32 v38, 0
	s_cbranch_vccnz .LBB0_407
	v_or_b32_e32 v33, 52, v32
	s_waitcnt lgkmcnt(0)
	v_mad_i64_i32 v[40:41], s[22:23], v33, s19, v[36:37]
	global_load_dword v38, v[40:41], off nt
.LBB0_407:
	s_and_b64 vcc, exec, s[4:5]
	s_cbranch_vccnz .LBB0_409
	v_or_b32_e32 v33, 54, v32
	s_waitcnt lgkmcnt(0)
	v_mad_i64_i32 v[40:41], s[22:23], v33, s19, v[36:37]
	global_load_dword v39, v[40:41], off nt
.LBB0_409:
	s_waitcnt lgkmcnt(0)
	v_mov_b32_e32 v41, 0
	s_and_b64 vcc, exec, s[4:5]
	v_mov_b32_e32 v40, 0
	s_cbranch_vccnz .LBB0_411
	v_or_b32_e32 v33, 56, v32
	v_mad_i64_i32 v[42:43], s[22:23], v33, s19, v[36:37]
	global_load_dword v40, v[42:43], off nt
.LBB0_411:
	s_and_b64 vcc, exec, s[4:5]
	s_cbranch_vccnz .LBB0_413
	v_or_b32_e32 v33, 58, v32
	v_mad_i64_i32 v[42:43], s[22:23], v33, s19, v[36:37]
	global_load_dword v41, v[42:43], off nt
.LBB0_413:
	v_mov_b32_e32 v43, 0
	s_and_b64 vcc, exec, s[4:5]
	v_mov_b32_e32 v42, 0
	s_cbranch_vccnz .LBB0_415
	v_or_b32_e32 v33, 60, v32
	v_mad_i64_i32 v[54:55], s[22:23], v33, s19, v[36:37]
	global_load_dword v42, v[54:55], off nt
.LBB0_415:
	s_and_b64 vcc, exec, s[4:5]
	s_cbranch_vccnz .LBB0_417
	v_or_b32_e32 v33, 62, v32
	v_mad_i64_i32 v[36:37], s[22:23], v33, s19, v[36:37]
	global_load_dword v43, v[36:37], off nt
.LBB0_417:
	s_andn2_b64 vcc, exec, s[12:13]
	s_cbranch_vccnz .LBB0_352
	v_readlane_b32 s36, v238, 21
	v_ashrrev_i32_e32 v33, 31, v32
	v_readlane_b32 s40, v238, 25
	v_readlane_b32 s41, v238, 26
	v_readlane_b32 s37, v238, 22
	v_readlane_b32 s38, v238, 23
	v_lshl_add_u64 v[32:33], v[32:33], 2, s[40:41]
	global_load_dword v36, v[32:33], off nt
	global_load_dword v37, v[32:33], off offset:8
	global_load_dword v54, v[32:33], off offset:16
	global_load_dword v55, v[32:33], off offset:24
	global_load_dword v56, v[32:33], off offset:32
	global_load_dword v57, v[32:33], off offset:40
	global_load_dword v58, v[32:33], off offset:48
	global_load_dword v59, v[32:33], off offset:56
	global_load_dword v60, v[32:33], off offset:64
	global_load_dword v61, v[32:33], off offset:72
	global_load_dword v62, v[32:33], off offset:80
	global_load_dword v63, v[32:33], off offset:88
	global_load_dword v64, v[32:33], off offset:96
	global_load_dword v65, v[32:33], off offset:104
	global_load_dword v66, v[32:33], off offset:112
	global_load_dword v67, v[32:33], off offset:120
	global_load_dword v68, v[32:33], off offset:128
	global_load_dword v69, v[32:33], off offset:136
	global_load_dword v70, v[32:33], off offset:144
	global_load_dword v71, v[32:33], off offset:152
	global_load_dword v72, v[32:33], off offset:160
	global_load_dword v73, v[32:33], off offset:168
	global_load_dword v74, v[32:33], off offset:176
	global_load_dword v75, v[32:33], off offset:184
	global_load_dword v76, v[32:33], off offset:192
	global_load_dword v77, v[32:33], off offset:200
	global_load_dword v78, v[32:33], off offset:208
	global_load_dword v79, v[32:33], off offset:216
	global_load_dword v80, v[32:33], off offset:224
	global_load_dword v81, v[32:33], off offset:232
	global_load_dword v82, v[32:33], off offset:240
	global_load_dword v83, v[32:33], off offset:248
	v_readlane_b32 s39, v238, 24
	v_readlane_b32 s42, v238, 27
	v_readlane_b32 s43, v238, 28
	v_readlane_b32 s44, v238, 29
	v_readlane_b32 s45, v238, 30
	v_readlane_b32 s46, v238, 31
	v_readlane_b32 s47, v238, 32
	v_readlane_b32 s48, v238, 33
	v_readlane_b32 s49, v238, 34
	v_readlane_b32 s50, v238, 35
	v_readlane_b32 s51, v238, 36
	s_waitcnt vmcnt(30)
	v_pk_mul_f32 v[8:9], v[8:9], v[36:37]
	s_waitcnt vmcnt(28)
	v_pk_mul_f32 v[10:11], v[10:11], v[54:55]
	s_waitcnt vmcnt(26)
	v_pk_mul_f32 v[12:13], v[12:13], v[56:57]
	s_waitcnt vmcnt(24)
	v_pk_mul_f32 v[14:15], v[14:15], v[58:59]
	s_waitcnt vmcnt(22)
	v_pk_mul_f32 v[16:17], v[16:17], v[60:61]
	s_waitcnt vmcnt(20)
	v_pk_mul_f32 v[18:19], v[18:19], v[62:63]
	s_waitcnt vmcnt(18)
	v_pk_mul_f32 v[20:21], v[20:21], v[64:65]
	s_waitcnt vmcnt(16)
	v_pk_mul_f32 v[22:23], v[22:23], v[66:67]
	s_waitcnt vmcnt(14)
	v_pk_mul_f32 v[24:25], v[24:25], v[68:69]
	s_waitcnt vmcnt(12)
	v_pk_mul_f32 v[26:27], v[26:27], v[70:71]
	s_waitcnt vmcnt(10)
	v_pk_mul_f32 v[28:29], v[28:29], v[72:73]
	s_waitcnt vmcnt(8)
	v_pk_mul_f32 v[30:31], v[30:31], v[74:75]
	s_waitcnt vmcnt(6)
	v_pk_mul_f32 v[34:35], v[34:35], v[76:77]
	s_waitcnt vmcnt(4)
	v_pk_mul_f32 v[38:39], v[38:39], v[78:79]
	s_waitcnt vmcnt(2)
	v_pk_mul_f32 v[40:41], v[40:41], v[80:81]
	s_waitcnt vmcnt(0)
	v_pk_mul_f32 v[42:43], v[42:43], v[82:83]
	s_branch .LBB0_352

.LBB0_423:
	v_ashrrev_i32_e32 v6, 31, v12
	v_lshrrev_b32_e32 v6, 27, v6
	v_add_u32_e32 v6, v12, v6
	v_ashrrev_i32_e32 v7, 5, v6
	v_lshlrev_b32_e32 v6, 6, v7
	v_lshlrev_b32_e32 v7, 10, v7
	v_add_u32_e32 v8, v48, v13
	v_sub_u32_e32 v8, v8, v7
	v_readlane_b32 s36, v238, 37
	v_ashrrev_i32_e32 v9, 31, v8
	v_readlane_b32 s38, v238, 39
	v_readlane_b32 s39, v238, 40
	v_or_b32_e32 v10, v6, v1
	v_mov_b32_e32 v14, 0
	v_lshl_add_u64 v[8:9], v[8:9], 2, s[38:39]
	s_and_b64 vcc, exec, s[4:5]
	v_mov_b32_e32 v11, 0
	v_readlane_b32 s37, v238, 38
	v_readlane_b32 s40, v238, 41
	v_readlane_b32 s41, v238, 42
	v_readlane_b32 s42, v238, 43
	v_readlane_b32 s43, v238, 44
	v_readlane_b32 s44, v238, 45
	v_readlane_b32 s45, v238, 46
	v_readlane_b32 s46, v238, 47
	v_readlane_b32 s47, v238, 48
	v_readlane_b32 s48, v238, 49
	v_readlane_b32 s49, v238, 50
	v_readlane_b32 s50, v238, 51
	v_readlane_b32 s51, v238, 52
	s_cbranch_vccnz .LBB0_425
	v_ashrrev_i32_e32 v11, 31, v10
	v_lshlrev_b64 v[16:17], 12, v[10:11]
	v_lshl_add_u64 v[16:17], v[8:9], 0, v[16:17]
	global_load_dword v11, v[16:17], off nt
.LBB0_425:
	s_and_b64 vcc, exec, s[4:5]
	s_cbranch_vccnz .LBB0_427
	v_or_b32_e32 v14, 2, v10
	v_ashrrev_i32_e32 v15, 31, v14
	v_lshlrev_b64 v[14:15], 12, v[14:15]
	v_lshl_add_u64 v[14:15], v[8:9], 0, v[14:15]
	global_load_dword v14, v[14:15], off nt
.LBB0_427:
	v_mov_b32_e32 v15, 0
	s_and_b64 vcc, exec, s[4:5]
	v_mov_b32_e32 v16, 0
	s_cbranch_vccnz .LBB0_429
	v_or_b32_e32 v16, 4, v10
	v_ashrrev_i32_e32 v17, 31, v16
	v_lshlrev_b64 v[16:17], 12, v[16:17]
	v_lshl_add_u64 v[16:17], v[8:9], 0, v[16:17]
	global_load_dword v16, v[16:17], off nt
.LBB0_429:
	s_and_b64 vcc, exec, s[4:5]
	s_cbranch_vccnz .LBB0_431
	v_or_b32_e32 v18, 6, v10
	v_ashrrev_i32_e32 v19, 31, v18
	v_lshlrev_b64 v[18:19], 12, v[18:19]
	v_lshl_add_u64 v[18:19], v[8:9], 0, v[18:19]
	global_load_dword v15, v[18:19], off nt
.LBB0_431:
	v_mov_b32_e32 v17, 0
	s_and_b64 vcc, exec, s[4:5]
	v_mov_b32_e32 v18, 0
	s_cbranch_vccnz .LBB0_433
	v_or_b32_e32 v18, 8, v10
	v_ashrrev_i32_e32 v19, 31, v18
	v_lshlrev_b64 v[18:19], 12, v[18:19]
	v_lshl_add_u64 v[18:19], v[8:9], 0, v[18:19]
	global_load_dword v18, v[18:19], off nt
.LBB0_433:
	s_and_b64 vcc, exec, s[4:5]
	s_cbranch_vccnz .LBB0_435
	v_or_b32_e32 v20, 10, v10
	v_ashrrev_i32_e32 v21, 31, v20
	v_lshlrev_b64 v[20:21], 12, v[20:21]
	v_lshl_add_u64 v[20:21], v[8:9], 0, v[20:21]
	global_load_dword v17, v[20:21], off nt
.LBB0_435:
	v_mov_b32_e32 v19, 0
	s_and_b64 vcc, exec, s[4:5]
	v_mov_b32_e32 v20, 0
	s_cbranch_vccnz .LBB0_437
	v_or_b32_e32 v20, 12, v10
	v_ashrrev_i32_e32 v21, 31, v20
	v_lshlrev_b64 v[20:21], 12, v[20:21]
	v_lshl_add_u64 v[20:21], v[8:9], 0, v[20:21]
	global_load_dword v20, v[20:21], off nt
.LBB0_437:
	s_and_b64 vcc, exec, s[4:5]
	s_cbranch_vccnz .LBB0_439
	v_or_b32_e32 v22, 14, v10
	v_ashrrev_i32_e32 v23, 31, v22
	v_lshlrev_b64 v[22:23], 12, v[22:23]
	v_lshl_add_u64 v[22:23], v[8:9], 0, v[22:23]
	global_load_dword v19, v[22:23], off nt
.LBB0_439:
	v_mov_b32_e32 v21, 0
	s_and_b64 vcc, exec, s[4:5]
	v_mov_b32_e32 v22, 0
	s_cbranch_vccnz .LBB0_441
	v_or_b32_e32 v22, 16, v10
	v_ashrrev_i32_e32 v23, 31, v22
	v_lshlrev_b64 v[22:23], 12, v[22:23]
	v_lshl_add_u64 v[22:23], v[8:9], 0, v[22:23]
	global_load_dword v22, v[22:23], off nt
.LBB0_441:
	s_and_b64 vcc, exec, s[4:5]
	s_cbranch_vccnz .LBB0_443
	v_or_b32_e32 v24, 18, v10
	v_ashrrev_i32_e32 v25, 31, v24
	v_lshlrev_b64 v[24:25], 12, v[24:25]
	v_lshl_add_u64 v[24:25], v[8:9], 0, v[24:25]
	global_load_dword v21, v[24:25], off nt
.LBB0_443:
	v_mov_b32_e32 v23, 0
	s_and_b64 vcc, exec, s[4:5]
	v_mov_b32_e32 v24, 0
	s_cbranch_vccnz .LBB0_445
	v_or_b32_e32 v24, 20, v10
	v_ashrrev_i32_e32 v25, 31, v24
	v_lshlrev_b64 v[24:25], 12, v[24:25]
	v_lshl_add_u64 v[24:25], v[8:9], 0, v[24:25]
	global_load_dword v24, v[24:25], off nt
.LBB0_445:
	s_and_b64 vcc, exec, s[4:5]
	s_cbranch_vccnz .LBB0_447
	v_or_b32_e32 v26, 22, v10
	v_ashrrev_i32_e32 v27, 31, v26
	v_lshlrev_b64 v[26:27], 12, v[26:27]
	v_lshl_add_u64 v[26:27], v[8:9], 0, v[26:27]
	global_load_dword v23, v[26:27], off nt
.LBB0_447:
	v_mov_b32_e32 v25, 0
	s_and_b64 vcc, exec, s[4:5]
	v_mov_b32_e32 v26, 0
	s_cbranch_vccnz .LBB0_449
	v_or_b32_e32 v26, 24, v10
	v_ashrrev_i32_e32 v27, 31, v26
	v_lshlrev_b64 v[26:27], 12, v[26:27]
	v_lshl_add_u64 v[26:27], v[8:9], 0, v[26:27]
	global_load_dword v26, v[26:27], off nt
.LBB0_449:
	s_and_b64 vcc, exec, s[4:5]
	s_cbranch_vccnz .LBB0_451
	v_or_b32_e32 v28, 26, v10
	v_ashrrev_i32_e32 v29, 31, v28
	v_lshlrev_b64 v[28:29], 12, v[28:29]
	v_lshl_add_u64 v[28:29], v[8:9], 0, v[28:29]
	global_load_dword v25, v[28:29], off nt
.LBB0_451:
	v_mov_b32_e32 v27, 0
	s_and_b64 vcc, exec, s[4:5]
	v_mov_b32_e32 v28, 0
	s_cbranch_vccnz .LBB0_453
	v_or_b32_e32 v28, 28, v10
	v_ashrrev_i32_e32 v29, 31, v28
	v_lshlrev_b64 v[28:29], 12, v[28:29]
	v_lshl_add_u64 v[28:29], v[8:9], 0, v[28:29]
	global_load_dword v28, v[28:29], off nt
.LBB0_453:
	s_and_b64 vcc, exec, s[4:5]
	s_cbranch_vccnz .LBB0_455
	v_or_b32_e32 v30, 30, v10
	v_ashrrev_i32_e32 v31, 31, v30
	v_lshlrev_b64 v[30:31], 12, v[30:31]
	v_lshl_add_u64 v[30:31], v[8:9], 0, v[30:31]
	global_load_dword v27, v[30:31], off nt
.LBB0_455:
	v_mov_b32_e32 v29, 0
	s_and_b64 vcc, exec, s[4:5]
	v_mov_b32_e32 v30, 0
	s_cbranch_vccnz .LBB0_457
	v_or_b32_e32 v30, 32, v10
	v_ashrrev_i32_e32 v31, 31, v30
	v_lshlrev_b64 v[30:31], 12, v[30:31]
	v_lshl_add_u64 v[30:31], v[8:9], 0, v[30:31]
	global_load_dword v30, v[30:31], off nt
.LBB0_457:
	s_and_b64 vcc, exec, s[4:5]
	s_cbranch_vccnz .LBB0_459
	v_or_b32_e32 v32, 34, v10
	v_ashrrev_i32_e32 v33, 31, v32
	v_lshlrev_b64 v[32:33], 12, v[32:33]
	v_lshl_add_u64 v[32:33], v[8:9], 0, v[32:33]
	global_load_dword v29, v[32:33], off nt
.LBB0_459:
	v_mov_b32_e32 v31, 0
	s_and_b64 vcc, exec, s[4:5]
	v_mov_b32_e32 v32, 0
	s_cbranch_vccnz .LBB0_461
	v_or_b32_e32 v32, 36, v10
	v_ashrrev_i32_e32 v33, 31, v32
	v_lshlrev_b64 v[32:33], 12, v[32:33]
	v_lshl_add_u64 v[32:33], v[8:9], 0, v[32:33]
	global_load_dword v32, v[32:33], off nt
.LBB0_461:
	s_and_b64 vcc, exec, s[4:5]
	s_cbranch_vccnz .LBB0_463
	v_or_b32_e32 v34, 38, v10
	v_ashrrev_i32_e32 v35, 31, v34
	v_lshlrev_b64 v[34:35], 12, v[34:35]
	v_lshl_add_u64 v[34:35], v[8:9], 0, v[34:35]
	global_load_dword v31, v[34:35], off nt
.LBB0_463:
	v_mov_b32_e32 v33, 0
	s_and_b64 vcc, exec, s[4:5]
	v_mov_b32_e32 v34, 0
	s_cbranch_vccnz .LBB0_465
	v_or_b32_e32 v34, 40, v10
	v_ashrrev_i32_e32 v35, 31, v34
	v_lshlrev_b64 v[34:35], 12, v[34:35]
	v_lshl_add_u64 v[34:35], v[8:9], 0, v[34:35]
	global_load_dword v34, v[34:35], off nt
.LBB0_465:
	s_and_b64 vcc, exec, s[4:5]
	s_cbranch_vccnz .LBB0_467
	v_or_b32_e32 v36, 42, v10
	v_ashrrev_i32_e32 v37, 31, v36
	v_lshlrev_b64 v[36:37], 12, v[36:37]
	v_lshl_add_u64 v[36:37], v[8:9], 0, v[36:37]
	global_load_dword v33, v[36:37], off nt
.LBB0_467:
	v_mov_b32_e32 v35, 0
	s_and_b64 vcc, exec, s[4:5]
	v_mov_b32_e32 v36, 0
	s_cbranch_vccnz .LBB0_469
	v_or_b32_e32 v36, 44, v10
	v_ashrrev_i32_e32 v37, 31, v36
	v_lshlrev_b64 v[36:37], 12, v[36:37]
	v_lshl_add_u64 v[36:37], v[8:9], 0, v[36:37]
	global_load_dword v36, v[36:37], off nt
.LBB0_469:
	s_and_b64 vcc, exec, s[4:5]
	s_cbranch_vccnz .LBB0_471
	v_or_b32_e32 v38, 46, v10
	v_ashrrev_i32_e32 v39, 31, v38
	v_lshlrev_b64 v[38:39], 12, v[38:39]
	v_lshl_add_u64 v[38:39], v[8:9], 0, v[38:39]
	global_load_dword v35, v[38:39], off nt
.LBB0_471:
	v_mov_b32_e32 v37, 0
	s_and_b64 vcc, exec, s[4:5]
	v_mov_b32_e32 v38, 0
	s_cbranch_vccnz .LBB0_473
	v_or_b32_e32 v38, 48, v10
	v_ashrrev_i32_e32 v39, 31, v38
	v_lshlrev_b64 v[38:39], 12, v[38:39]
	v_lshl_add_u64 v[38:39], v[8:9], 0, v[38:39]
	global_load_dword v38, v[38:39], off nt
.LBB0_473:
	s_and_b64 vcc, exec, s[4:5]
	s_cbranch_vccnz .LBB0_475
	v_or_b32_e32 v40, 50, v10
	s_waitcnt lgkmcnt(0)
	v_ashrrev_i32_e32 v41, 31, v40
	v_lshlrev_b64 v[40:41], 12, v[40:41]
	v_lshl_add_u64 v[40:41], v[8:9], 0, v[40:41]
	global_load_dword v37, v[40:41], off nt
.LBB0_475:
	v_mov_b32_e32 v39, 0
	s_and_b64 vcc, exec, s[4:5]
	v_mov_b32_e32 v40, 0
	s_cbranch_vccnz .LBB0_477
	v_or_b32_e32 v40, 52, v10
	s_waitcnt lgkmcnt(0)
	v_ashrrev_i32_e32 v41, 31, v40
	v_lshlrev_b64 v[40:41], 12, v[40:41]
	v_lshl_add_u64 v[40:41], v[8:9], 0, v[40:41]
	global_load_dword v40, v[40:41], off nt
.LBB0_477:
	s_and_b64 vcc, exec, s[4:5]
	s_cbranch_vccnz .LBB0_479
	v_or_b32_e32 v42, 54, v10
	v_ashrrev_i32_e32 v43, 31, v42
	v_lshlrev_b64 v[42:43], 12, v[42:43]
	v_lshl_add_u64 v[42:43], v[8:9], 0, v[42:43]
	global_load_dword v39, v[42:43], off nt
.LBB0_479:
	s_waitcnt lgkmcnt(0)
	v_mov_b32_e32 v41, 0
	s_and_b64 vcc, exec, s[4:5]
	v_mov_b32_e32 v42, 0
	s_cbranch_vccnz .LBB0_481
	v_or_b32_e32 v42, 56, v10
	v_ashrrev_i32_e32 v43, 31, v42
	v_lshlrev_b64 v[42:43], 12, v[42:43]
	v_lshl_add_u64 v[42:43], v[8:9], 0, v[42:43]
	global_load_dword v42, v[42:43], off nt
.LBB0_481:
	s_and_b64 vcc, exec, s[4:5]
	s_cbranch_vccnz .LBB0_483
	v_or_b32_e32 v44, 58, v10
	v_ashrrev_i32_e32 v45, 31, v44
	v_lshlrev_b64 v[44:45], 12, v[44:45]
	v_lshl_add_u64 v[44:45], v[8:9], 0, v[44:45]
	global_load_dword v41, v[44:45], off nt
.LBB0_483:
	v_mov_b32_e32 v43, 0
	s_and_b64 vcc, exec, s[4:5]
	v_mov_b32_e32 v44, 0
	s_cbranch_vccnz .LBB0_485
	v_or_b32_e32 v44, 60, v10
	v_ashrrev_i32_e32 v45, 31, v44
	v_lshlrev_b64 v[44:45], 12, v[44:45]
	v_lshl_add_u64 v[44:45], v[8:9], 0, v[44:45]
	global_load_dword v44, v[44:45], off nt
.LBB0_485:
	s_and_b64 vcc, exec, s[4:5]
	s_cbranch_vccnz .LBB0_422
	v_or_b32_e32 v52, 62, v10
	v_ashrrev_i32_e32 v53, 31, v52
	v_lshlrev_b64 v[52:53], 12, v[52:53]
	v_lshl_add_u64 v[8:9], v[8:9], 0, v[52:53]
	global_load_dword v43, v[8:9], off nt
	s_branch .LBB0_422

.LBB0_491:
	v_ashrrev_i32_e32 v6, 31, v12
	v_lshrrev_b32_e32 v6, 27, v6
	v_add_u32_e32 v6, v12, v6
	v_ashrrev_i32_e32 v7, 5, v6
	v_lshlrev_b32_e32 v6, 6, v7
	v_lshlrev_b32_e32 v7, 10, v7
	v_add_u32_e32 v8, v48, v13
	v_sub_u32_e32 v8, v8, v7
	v_readlane_b32 s36, v238, 37
	v_ashrrev_i32_e32 v9, 31, v8
	v_readlane_b32 s40, v238, 41
	v_readlane_b32 s41, v238, 42
	v_or_b32_e32 v10, v6, v1
	v_mov_b32_e32 v14, 0
	v_lshl_add_u64 v[8:9], v[8:9], 2, s[40:41]
	s_and_b64 vcc, exec, s[4:5]
	v_mov_b32_e32 v11, 0
	v_readlane_b32 s37, v238, 38
	v_readlane_b32 s38, v238, 39
	v_readlane_b32 s39, v238, 40
	v_readlane_b32 s42, v238, 43
	v_readlane_b32 s43, v238, 44
	v_readlane_b32 s44, v238, 45
	v_readlane_b32 s45, v238, 46
	v_readlane_b32 s46, v238, 47
	v_readlane_b32 s47, v238, 48
	v_readlane_b32 s48, v238, 49
	v_readlane_b32 s49, v238, 50
	v_readlane_b32 s50, v238, 51
	v_readlane_b32 s51, v238, 52
	s_cbranch_vccnz .LBB0_493
	v_ashrrev_i32_e32 v11, 31, v10
	v_lshlrev_b64 v[16:17], 12, v[10:11]
	v_lshl_add_u64 v[16:17], v[8:9], 0, v[16:17]
	global_load_dword v11, v[16:17], off nt

.LBB0_559:
	v_ashrrev_i32_e32 v6, 31, v12
	v_lshrrev_b32_e32 v6, 27, v6
	v_add_u32_e32 v6, v12, v6
	v_ashrrev_i32_e32 v7, 5, v6
	v_lshlrev_b32_e32 v6, 6, v7
	v_lshlrev_b32_e32 v7, 10, v7
	v_add_u32_e32 v8, v48, v13
	v_sub_u32_e32 v8, v8, v7
	v_readlane_b32 s36, v238, 37
	v_ashrrev_i32_e32 v9, 31, v8
	v_readlane_b32 s42, v238, 43
	v_readlane_b32 s43, v238, 44
	v_or_b32_e32 v10, v6, v1
	v_mov_b32_e32 v14, 0
	v_lshl_add_u64 v[8:9], v[8:9], 2, s[42:43]
	s_and_b64 vcc, exec, s[4:5]
	v_mov_b32_e32 v11, 0
	v_readlane_b32 s37, v238, 38
	v_readlane_b32 s38, v238, 39
	v_readlane_b32 s39, v238, 40
	v_readlane_b32 s40, v238, 41
	v_readlane_b32 s41, v238, 42
	v_readlane_b32 s44, v238, 45
	v_readlane_b32 s45, v238, 46
	v_readlane_b32 s46, v238, 47
	v_readlane_b32 s47, v238, 48
	v_readlane_b32 s48, v238, 49
	v_readlane_b32 s49, v238, 50
	v_readlane_b32 s50, v238, 51
	v_readlane_b32 s51, v238, 52
	s_cbranch_vccnz .LBB0_561
	v_ashrrev_i32_e32 v11, 31, v10
	v_lshlrev_b64 v[16:17], 12, v[10:11]
	v_lshl_add_u64 v[16:17], v[8:9], 0, v[16:17]
	global_load_dword v11, v[16:17], off nt

.LBB0_627:
	v_mul_hi_i32 v8, v7, s15
	v_lshrrev_b32_e32 v9, 31, v8
	v_ashrrev_i32_e32 v8, 5, v8
	v_add_u32_e32 v9, v8, v9
	v_mul_lo_u32 v56, v9, s18
	v_add_u32_e32 v12, v51, v56
	v_mad_u64_u32 v[10:11], s[8:9], v9, s19, v[6:7]
	v_lshlrev_b32_e32 v8, 6, v9
	v_and_b32_e32 v9, 0xffffff80, v10
	v_and_b32_e32 v10, 0x60, v12
	v_or3_b32 v10, v10, v9, v48
	v_and_b32_e32 v9, 4, v7
	v_cmp_eq_u32_e32 vcc, 0, v9
	v_ashrrev_i32_e32 v11, 31, v10
	v_or_b32_e32 v28, v8, v1
	v_cndmask_b32_e32 v13, v52, v53, vcc
	v_cndmask_b32_e32 v12, v54, v55, vcc
	v_lshl_add_u64 v[32:33], v[10:11], 2, v[12:13]
	v_cmp_ne_u64_e32 vcc, 0, v[12:13]
	v_mov_b32_e32 v11, 0
	v_mov_b32_e32 v10, 0
	s_and_saveexec_b64 s[8:9], vcc
	s_cbranch_execz .LBB0_629
	v_mad_i64_i32 v[12:13], s[22:23], v28, s20, v[32:33]
	global_load_dword v10, v[12:13], off nt
.LBB0_629:
	s_or_b64 exec, exec, s[8:9]
	s_and_saveexec_b64 s[8:9], vcc
	s_cbranch_execz .LBB0_631
	v_or_b32_e32 v9, 2, v28
	v_mad_i64_i32 v[12:13], s[22:23], v9, s20, v[32:33]
	global_load_dword v11, v[12:13], off nt
.LBB0_631:
	s_or_b64 exec, exec, s[8:9]
	v_mov_b32_e32 v13, 0
	v_mov_b32_e32 v12, 0
	s_and_saveexec_b64 s[8:9], vcc
	s_cbranch_execz .LBB0_633
	v_or_b32_e32 v9, 4, v28
	v_mad_i64_i32 v[14:15], s[22:23], v9, s20, v[32:33]
	global_load_dword v12, v[14:15], off nt
.LBB0_633:
	s_or_b64 exec, exec, s[8:9]
	s_and_saveexec_b64 s[8:9], vcc
	s_cbranch_execz .LBB0_635
	v_or_b32_e32 v9, 6, v28
	v_mad_i64_i32 v[14:15], s[22:23], v9, s20, v[32:33]
	global_load_dword v13, v[14:15], off nt
.LBB0_635:
	s_or_b64 exec, exec, s[8:9]
	v_mov_b32_e32 v15, 0
	v_mov_b32_e32 v14, 0
	s_and_saveexec_b64 s[8:9], vcc
	s_cbranch_execz .LBB0_637
	v_or_b32_e32 v9, 8, v28
	v_mad_i64_i32 v[16:17], s[22:23], v9, s20, v[32:33]
	global_load_dword v14, v[16:17], off nt
.LBB0_637:
	s_or_b64 exec, exec, s[8:9]
	s_and_saveexec_b64 s[8:9], vcc
	s_cbranch_execz .LBB0_639
	v_or_b32_e32 v9, 10, v28
	v_mad_i64_i32 v[16:17], s[22:23], v9, s20, v[32:33]
	global_load_dword v15, v[16:17], off nt
.LBB0_639:
	s_or_b64 exec, exec, s[8:9]
	v_mov_b32_e32 v17, 0
	v_mov_b32_e32 v16, 0
	s_and_saveexec_b64 s[8:9], vcc
	s_cbranch_execz .LBB0_641
	v_or_b32_e32 v9, 12, v28
	v_mad_i64_i32 v[18:19], s[22:23], v9, s20, v[32:33]
	global_load_dword v16, v[18:19], off nt
.LBB0_641:
	s_or_b64 exec, exec, s[8:9]
	s_and_saveexec_b64 s[8:9], vcc
	s_cbranch_execz .LBB0_643
	v_or_b32_e32 v9, 14, v28
	v_mad_i64_i32 v[18:19], s[22:23], v9, s20, v[32:33]
	global_load_dword v17, v[18:19], off nt
.LBB0_643:
	s_or_b64 exec, exec, s[8:9]
	v_mov_b32_e32 v19, 0
	v_mov_b32_e32 v18, 0
	s_and_saveexec_b64 s[8:9], vcc
	s_cbranch_execz .LBB0_645
	v_or_b32_e32 v9, 16, v28
	v_mad_i64_i32 v[20:21], s[22:23], v9, s20, v[32:33]
	global_load_dword v18, v[20:21], off nt
.LBB0_645:
	s_or_b64 exec, exec, s[8:9]
	s_and_saveexec_b64 s[8:9], vcc
	s_cbranch_execz .LBB0_647
	v_or_b32_e32 v9, 18, v28
	v_mad_i64_i32 v[20:21], s[22:23], v9, s20, v[32:33]
	global_load_dword v19, v[20:21], off nt
.LBB0_647:
	s_or_b64 exec, exec, s[8:9]
	v_mov_b32_e32 v21, 0
	v_mov_b32_e32 v20, 0
	s_and_saveexec_b64 s[8:9], vcc
	s_cbranch_execz .LBB0_649
	v_or_b32_e32 v9, 20, v28
	v_mad_i64_i32 v[22:23], s[22:23], v9, s20, v[32:33]
	global_load_dword v20, v[22:23], off nt
.LBB0_649:
	s_or_b64 exec, exec, s[8:9]
	s_and_saveexec_b64 s[8:9], vcc
	s_cbranch_execz .LBB0_651
	v_or_b32_e32 v9, 22, v28
	v_mad_i64_i32 v[22:23], s[22:23], v9, s20, v[32:33]
	global_load_dword v21, v[22:23], off nt
.LBB0_651:
	s_or_b64 exec, exec, s[8:9]
	v_mov_b32_e32 v23, 0
	v_mov_b32_e32 v22, 0
	s_and_saveexec_b64 s[8:9], vcc
	s_cbranch_execz .LBB0_653
	v_or_b32_e32 v9, 24, v28
	v_mad_i64_i32 v[24:25], s[22:23], v9, s20, v[32:33]
	global_load_dword v22, v[24:25], off nt
.LBB0_653:
	s_or_b64 exec, exec, s[8:9]
	s_and_saveexec_b64 s[8:9], vcc
	s_cbranch_execz .LBB0_655
	v_or_b32_e32 v9, 26, v28
	v_mad_i64_i32 v[24:25], s[22:23], v9, s20, v[32:33]
	global_load_dword v23, v[24:25], off nt
.LBB0_655:
	s_or_b64 exec, exec, s[8:9]
	v_mov_b32_e32 v25, 0
	v_mov_b32_e32 v24, 0
	s_and_saveexec_b64 s[8:9], vcc
	s_cbranch_execz .LBB0_657
	v_or_b32_e32 v9, 28, v28
	v_mad_i64_i32 v[26:27], s[22:23], v9, s20, v[32:33]
	global_load_dword v24, v[26:27], off nt
.LBB0_657:
	s_or_b64 exec, exec, s[8:9]
	s_and_saveexec_b64 s[8:9], vcc
	s_cbranch_execz .LBB0_659
	v_or_b32_e32 v9, 30, v28
	v_mad_i64_i32 v[26:27], s[22:23], v9, s20, v[32:33]
	global_load_dword v25, v[26:27], off nt
.LBB0_659:
	s_or_b64 exec, exec, s[8:9]
	v_mov_b32_e32 v27, 0
	v_mov_b32_e32 v26, 0
	s_and_saveexec_b64 s[8:9], vcc
	s_cbranch_execz .LBB0_661
	v_or_b32_e32 v9, 32, v28
	v_mad_i64_i32 v[30:31], s[22:23], v9, s20, v[32:33]
	global_load_dword v26, v[30:31], off nt
.LBB0_661:
	s_or_b64 exec, exec, s[8:9]
	s_and_saveexec_b64 s[8:9], vcc
	s_cbranch_execz .LBB0_663
	v_or_b32_e32 v9, 34, v28
	v_mad_i64_i32 v[30:31], s[22:23], v9, s20, v[32:33]
	global_load_dword v27, v[30:31], off nt
.LBB0_663:
	s_or_b64 exec, exec, s[8:9]
	v_mov_b32_e32 v31, 0
	v_mov_b32_e32 v30, 0
	s_and_saveexec_b64 s[8:9], vcc
	s_cbranch_execz .LBB0_665
	v_or_b32_e32 v9, 36, v28
	v_mad_i64_i32 v[34:35], s[22:23], v9, s20, v[32:33]
	global_load_dword v30, v[34:35], off nt
.LBB0_665:
	s_or_b64 exec, exec, s[8:9]
	s_and_saveexec_b64 s[8:9], vcc
	s_cbranch_execz .LBB0_667
	v_or_b32_e32 v9, 38, v28
	v_mad_i64_i32 v[34:35], s[22:23], v9, s20, v[32:33]
	global_load_dword v31, v[34:35], off nt
.LBB0_667:
	s_or_b64 exec, exec, s[8:9]
	v_mov_b32_e32 v35, 0
	v_mov_b32_e32 v34, 0
	s_and_saveexec_b64 s[8:9], vcc
	s_cbranch_execz .LBB0_669
	v_or_b32_e32 v9, 40, v28
	v_mad_i64_i32 v[36:37], s[22:23], v9, s20, v[32:33]
	global_load_dword v34, v[36:37], off nt
.LBB0_669:
	s_or_b64 exec, exec, s[8:9]
	s_and_saveexec_b64 s[8:9], vcc
	s_cbranch_execz .LBB0_671
	v_or_b32_e32 v9, 42, v28
	v_mad_i64_i32 v[36:37], s[22:23], v9, s20, v[32:33]
	global_load_dword v35, v[36:37], off nt
.LBB0_671:
	s_or_b64 exec, exec, s[8:9]
	v_mov_b32_e32 v37, 0
	v_mov_b32_e32 v36, 0
	s_and_saveexec_b64 s[8:9], vcc
	s_cbranch_execz .LBB0_673
	v_or_b32_e32 v9, 44, v28
	v_mad_i64_i32 v[38:39], s[22:23], v9, s20, v[32:33]
	global_load_dword v36, v[38:39], off nt
.LBB0_673:
	s_or_b64 exec, exec, s[8:9]
	s_and_saveexec_b64 s[8:9], vcc
	s_cbranch_execz .LBB0_675
	v_or_b32_e32 v9, 46, v28
	v_mad_i64_i32 v[38:39], s[22:23], v9, s20, v[32:33]
	global_load_dword v37, v[38:39], off nt
.LBB0_675:
	s_or_b64 exec, exec, s[8:9]
	v_mov_b32_e32 v39, 0
	v_mov_b32_e32 v38, 0
	s_and_saveexec_b64 s[8:9], vcc
	s_cbranch_execz .LBB0_677
	v_or_b32_e32 v9, 48, v28
	s_waitcnt lgkmcnt(0)
	v_mad_i64_i32 v[40:41], s[22:23], v9, s20, v[32:33]
	global_load_dword v38, v[40:41], off nt
.LBB0_677:
	s_or_b64 exec, exec, s[8:9]
	s_and_saveexec_b64 s[8:9], vcc
	s_cbranch_execz .LBB0_679
	v_or_b32_e32 v9, 50, v28
	s_waitcnt lgkmcnt(0)
	v_mad_i64_i32 v[40:41], s[22:23], v9, s20, v[32:33]
	global_load_dword v39, v[40:41], off nt
.LBB0_679:
	s_or_b64 exec, exec, s[8:9]
	s_waitcnt lgkmcnt(0)
	v_mov_b32_e32 v41, 0
	v_mov_b32_e32 v40, 0
	s_and_saveexec_b64 s[8:9], vcc
	s_cbranch_execz .LBB0_681
	v_or_b32_e32 v9, 52, v28
	v_mad_i64_i32 v[42:43], s[22:23], v9, s20, v[32:33]
	global_load_dword v40, v[42:43], off nt
.LBB0_681:
	s_or_b64 exec, exec, s[8:9]
	s_and_saveexec_b64 s[8:9], vcc
	s_cbranch_execz .LBB0_683
	v_or_b32_e32 v9, 54, v28
	v_mad_i64_i32 v[42:43], s[22:23], v9, s20, v[32:33]
	global_load_dword v41, v[42:43], off nt
.LBB0_683:
	s_or_b64 exec, exec, s[8:9]
	v_mov_b32_e32 v43, 0
	v_mov_b32_e32 v42, 0
	s_and_saveexec_b64 s[8:9], vcc
	s_cbranch_execz .LBB0_685
	v_or_b32_e32 v9, 56, v28
	v_mad_i64_i32 v[44:45], s[22:23], v9, s20, v[32:33]
	global_load_dword v42, v[44:45], off nt
.LBB0_685:
	s_or_b64 exec, exec, s[8:9]
	s_and_saveexec_b64 s[8:9], vcc
	s_cbranch_execz .LBB0_687
	v_or_b32_e32 v9, 58, v28
	v_mad_i64_i32 v[44:45], s[22:23], v9, s20, v[32:33]
	global_load_dword v43, v[44:45], off nt

.LBB0_690:
	v_or_b32_e32 v9, 60, v28
	v_mad_i64_i32 v[58:59], s[22:23], v9, s20, v[32:33]
	global_load_dword v44, v[58:59], off nt
	s_or_b64 exec, exec, s[8:9]
	s_and_saveexec_b64 s[8:9], vcc
	s_cbranch_execz .LBB0_689
.LBB0_691:
	v_or_b32_e32 v9, 62, v28
	v_mad_i64_i32 v[32:33], s[22:23], v9, s20, v[32:33]
	global_load_dword v45, v[32:33], off nt
	s_or_b64 exec, exec, s[8:9]
	s_andn2_b64 vcc, exec, s[6:7]
	s_cbranch_vccnz .LBB0_626
.LBB0_692:
	v_readlane_b32 s36, v238, 37
	v_ashrrev_i32_e32 v29, 31, v28
	v_readlane_b32 s44, v238, 45
	v_readlane_b32 s45, v238, 46
	v_readlane_b32 s37, v238, 38
	v_readlane_b32 s38, v238, 39
	v_lshl_add_u64 v[28:29], v[28:29], 2, s[44:45]
	global_load_dword v32, v[28:29], off nt
	global_load_dword v33, v[28:29], off offset:8
	global_load_dword v58, v[28:29], off offset:16
	global_load_dword v59, v[28:29], off offset:24
	global_load_dword v60, v[28:29], off offset:32
	global_load_dword v61, v[28:29], off offset:40
	global_load_dword v62, v[28:29], off offset:48
	global_load_dword v63, v[28:29], off offset:56
	global_load_dword v64, v[28:29], off offset:64
	global_load_dword v65, v[28:29], off offset:72
	global_load_dword v66, v[28:29], off offset:80
	global_load_dword v67, v[28:29], off offset:88
	global_load_dword v68, v[28:29], off offset:96
	global_load_dword v69, v[28:29], off offset:104
	global_load_dword v70, v[28:29], off offset:112
	global_load_dword v71, v[28:29], off offset:120
	global_load_dword v72, v[28:29], off offset:128
	global_load_dword v73, v[28:29], off offset:136
	global_load_dword v74, v[28:29], off offset:144
	global_load_dword v75, v[28:29], off offset:152
	global_load_dword v76, v[28:29], off offset:160
	global_load_dword v77, v[28:29], off offset:168
	global_load_dword v78, v[28:29], off offset:176
	global_load_dword v79, v[28:29], off offset:184
	global_load_dword v80, v[28:29], off offset:192
	global_load_dword v81, v[28:29], off offset:200
	global_load_dword v82, v[28:29], off offset:208
	global_load_dword v83, v[28:29], off offset:216
	global_load_dword v84, v[28:29], off offset:224
	global_load_dword v85, v[28:29], off offset:232
	global_load_dword v86, v[28:29], off offset:240
	global_load_dword v87, v[28:29], off offset:248
	v_readlane_b32 s39, v238, 40
	v_readlane_b32 s40, v238, 41
	v_readlane_b32 s41, v238, 42
	v_readlane_b32 s42, v238, 43
	v_readlane_b32 s43, v238, 44
	v_readlane_b32 s46, v238, 47
	v_readlane_b32 s47, v238, 48
	v_readlane_b32 s48, v238, 49
	v_readlane_b32 s49, v238, 50
	v_readlane_b32 s50, v238, 51
	v_readlane_b32 s51, v238, 52
	s_waitcnt vmcnt(30)
	v_pk_mul_f32 v[10:11], v[10:11], v[32:33]
	s_waitcnt vmcnt(28)
	v_pk_mul_f32 v[12:13], v[12:13], v[58:59]
	s_waitcnt vmcnt(26)
	v_pk_mul_f32 v[14:15], v[14:15], v[60:61]
	s_waitcnt vmcnt(24)
	v_pk_mul_f32 v[16:17], v[16:17], v[62:63]
	s_waitcnt vmcnt(22)
	v_pk_mul_f32 v[18:19], v[18:19], v[64:65]
	s_waitcnt vmcnt(20)
	v_pk_mul_f32 v[20:21], v[20:21], v[66:67]
	s_waitcnt vmcnt(18)
	v_pk_mul_f32 v[22:23], v[22:23], v[68:69]
	s_waitcnt vmcnt(16)
	v_pk_mul_f32 v[24:25], v[24:25], v[70:71]
	s_waitcnt vmcnt(14)
	v_pk_mul_f32 v[26:27], v[26:27], v[72:73]
	s_waitcnt vmcnt(12)
	v_pk_mul_f32 v[30:31], v[30:31], v[74:75]
	s_waitcnt vmcnt(10)
	v_pk_mul_f32 v[34:35], v[34:35], v[76:77]
	s_waitcnt vmcnt(8)
	v_pk_mul_f32 v[36:37], v[36:37], v[78:79]
	s_waitcnt vmcnt(6)
	v_pk_mul_f32 v[38:39], v[38:39], v[80:81]
	s_waitcnt vmcnt(4)
	v_pk_mul_f32 v[40:41], v[40:41], v[82:83]
	s_waitcnt vmcnt(2)
	v_pk_mul_f32 v[42:43], v[42:43], v[84:85]
	s_waitcnt vmcnt(0)
	v_pk_mul_f32 v[44:45], v[44:45], v[86:87]
	s_branch .LBB0_626

.LBB0_696:
	v_ashrrev_i32_e32 v6, 31, v5
	v_lshrrev_b32_e32 v6, 27, v6
	v_add_u32_e32 v6, v5, v6
	v_ashrrev_i32_e32 v13, 5, v6
	v_lshlrev_b32_e32 v7, 10, v13
	v_sub_u32_e32 v8, v12, v7
	v_readlane_b32 s36, v238, 37
	v_lshlrev_b32_e32 v6, 6, v13
	v_ashrrev_i32_e32 v9, 31, v8
	v_readlane_b32 s50, v238, 51
	v_readlane_b32 s51, v238, 52
	v_or_b32_e32 v10, v6, v1
	v_mov_b32_e32 v7, 0
	v_lshl_add_u64 v[8:9], v[8:9], 2, s[50:51]
	s_and_b64 vcc, exec, s[0:1]
	v_mov_b32_e32 v11, 0
	v_readlane_b32 s37, v238, 38
	v_readlane_b32 s38, v238, 39
	v_readlane_b32 s39, v238, 40
	v_readlane_b32 s40, v238, 41
	v_readlane_b32 s41, v238, 42
	v_readlane_b32 s42, v238, 43
	v_readlane_b32 s43, v238, 44
	v_readlane_b32 s44, v238, 45
	v_readlane_b32 s45, v238, 46
	v_readlane_b32 s46, v238, 47
	v_readlane_b32 s47, v238, 48
	v_readlane_b32 s48, v238, 49
	v_readlane_b32 s49, v238, 50
	s_cbranch_vccnz .LBB0_698
	v_ashrrev_i32_e32 v11, 31, v10
	v_lshlrev_b64 v[14:15], 12, v[10:11]
	v_lshl_add_u64 v[14:15], v[8:9], 0, v[14:15]
	global_load_dword v11, v[14:15], off nt
.LBB0_698:
	s_and_b64 vcc, exec, s[0:1]
	s_cbranch_vccnz .LBB0_700
	v_or_b32_e32 v14, 2, v10
	v_ashrrev_i32_e32 v15, 31, v14
	v_lshlrev_b64 v[14:15], 12, v[14:15]
	v_lshl_add_u64 v[14:15], v[8:9], 0, v[14:15]
	global_load_dword v7, v[14:15], off nt
.LBB0_700:
	v_mov_b32_e32 v14, 0
	s_and_b64 vcc, exec, s[0:1]
	v_mov_b32_e32 v15, 0
	s_cbranch_vccnz .LBB0_702
	v_or_b32_e32 v16, 4, v10
	v_ashrrev_i32_e32 v17, 31, v16
	v_lshlrev_b64 v[16:17], 12, v[16:17]
	v_lshl_add_u64 v[16:17], v[8:9], 0, v[16:17]
	global_load_dword v15, v[16:17], off nt
.LBB0_702:
	s_and_b64 vcc, exec, s[0:1]
	s_cbranch_vccnz .LBB0_704
	v_or_b32_e32 v16, 6, v10
	v_ashrrev_i32_e32 v17, 31, v16
	v_lshlrev_b64 v[16:17], 12, v[16:17]
	v_lshl_add_u64 v[16:17], v[8:9], 0, v[16:17]
	global_load_dword v14, v[16:17], off nt
.LBB0_704:
	v_mov_b32_e32 v16, 0
	s_and_b64 vcc, exec, s[0:1]
	v_mov_b32_e32 v17, 0
	s_cbranch_vccnz .LBB0_706
	v_or_b32_e32 v18, 8, v10
	v_ashrrev_i32_e32 v19, 31, v18
	v_lshlrev_b64 v[18:19], 12, v[18:19]
	v_lshl_add_u64 v[18:19], v[8:9], 0, v[18:19]
	global_load_dword v17, v[18:19], off nt
.LBB0_706:
	s_and_b64 vcc, exec, s[0:1]
	s_cbranch_vccnz .LBB0_708
	v_or_b32_e32 v18, 10, v10
	v_ashrrev_i32_e32 v19, 31, v18
	v_lshlrev_b64 v[18:19], 12, v[18:19]
	v_lshl_add_u64 v[18:19], v[8:9], 0, v[18:19]
	global_load_dword v16, v[18:19], off nt
.LBB0_708:
	v_mov_b32_e32 v18, 0
	s_and_b64 vcc, exec, s[0:1]
	v_mov_b32_e32 v19, 0
	s_cbranch_vccnz .LBB0_710
	v_or_b32_e32 v20, 12, v10
	v_ashrrev_i32_e32 v21, 31, v20
	v_lshlrev_b64 v[20:21], 12, v[20:21]
	v_lshl_add_u64 v[20:21], v[8:9], 0, v[20:21]
	global_load_dword v19, v[20:21], off nt
.LBB0_710:
	s_and_b64 vcc, exec, s[0:1]
	s_cbranch_vccnz .LBB0_712
	v_or_b32_e32 v20, 14, v10
	v_ashrrev_i32_e32 v21, 31, v20
	v_lshlrev_b64 v[20:21], 12, v[20:21]
	v_lshl_add_u64 v[20:21], v[8:9], 0, v[20:21]
	global_load_dword v18, v[20:21], off nt
.LBB0_712:
	v_mov_b32_e32 v20, 0
	s_and_b64 vcc, exec, s[0:1]
	v_mov_b32_e32 v21, 0
	s_cbranch_vccnz .LBB0_714
	v_or_b32_e32 v22, 16, v10
	v_ashrrev_i32_e32 v23, 31, v22
	v_lshlrev_b64 v[22:23], 12, v[22:23]
	v_lshl_add_u64 v[22:23], v[8:9], 0, v[22:23]
	global_load_dword v21, v[22:23], off nt
.LBB0_714:
	s_and_b64 vcc, exec, s[0:1]
	s_cbranch_vccnz .LBB0_716
	v_or_b32_e32 v22, 18, v10
	v_ashrrev_i32_e32 v23, 31, v22
	v_lshlrev_b64 v[22:23], 12, v[22:23]
	v_lshl_add_u64 v[22:23], v[8:9], 0, v[22:23]
	global_load_dword v20, v[22:23], off nt
.LBB0_716:
	v_mov_b32_e32 v22, 0
	s_and_b64 vcc, exec, s[0:1]
	v_mov_b32_e32 v23, 0
	s_cbranch_vccnz .LBB0_718
	v_or_b32_e32 v24, 20, v10
	v_ashrrev_i32_e32 v25, 31, v24
	v_lshlrev_b64 v[24:25], 12, v[24:25]
	v_lshl_add_u64 v[24:25], v[8:9], 0, v[24:25]
	global_load_dword v23, v[24:25], off nt
.LBB0_718:
	s_and_b64 vcc, exec, s[0:1]
	s_cbranch_vccnz .LBB0_720
	v_or_b32_e32 v24, 22, v10
	v_ashrrev_i32_e32 v25, 31, v24
	v_lshlrev_b64 v[24:25], 12, v[24:25]
	v_lshl_add_u64 v[24:25], v[8:9], 0, v[24:25]
	global_load_dword v22, v[24:25], off nt
.LBB0_720:
	v_mov_b32_e32 v24, 0
	s_and_b64 vcc, exec, s[0:1]
	v_mov_b32_e32 v25, 0
	s_cbranch_vccnz .LBB0_722
	v_or_b32_e32 v26, 24, v10
	v_ashrrev_i32_e32 v27, 31, v26
	v_lshlrev_b64 v[26:27], 12, v[26:27]
	v_lshl_add_u64 v[26:27], v[8:9], 0, v[26:27]
	global_load_dword v25, v[26:27], off nt
.LBB0_722:
	s_and_b64 vcc, exec, s[0:1]
	s_cbranch_vccnz .LBB0_724
	v_or_b32_e32 v26, 26, v10
	v_ashrrev_i32_e32 v27, 31, v26
	v_lshlrev_b64 v[26:27], 12, v[26:27]
	v_lshl_add_u64 v[26:27], v[8:9], 0, v[26:27]
	global_load_dword v24, v[26:27], off nt
.LBB0_724:
	v_mov_b32_e32 v26, 0
	s_and_b64 vcc, exec, s[0:1]
	v_mov_b32_e32 v27, 0
	s_cbranch_vccnz .LBB0_726
	v_or_b32_e32 v28, 28, v10
	v_ashrrev_i32_e32 v29, 31, v28
	v_lshlrev_b64 v[28:29], 12, v[28:29]
	v_lshl_add_u64 v[28:29], v[8:9], 0, v[28:29]
	global_load_dword v27, v[28:29], off nt
.LBB0_726:
	s_and_b64 vcc, exec, s[0:1]
	s_cbranch_vccnz .LBB0_728
	v_or_b32_e32 v28, 30, v10
	v_ashrrev_i32_e32 v29, 31, v28
	v_lshlrev_b64 v[28:29], 12, v[28:29]
	v_lshl_add_u64 v[28:29], v[8:9], 0, v[28:29]
	global_load_dword v26, v[28:29], off nt
.LBB0_728:
	v_mov_b32_e32 v28, 0
	s_and_b64 vcc, exec, s[0:1]
	v_mov_b32_e32 v29, 0
	s_cbranch_vccnz .LBB0_730
	v_or_b32_e32 v30, 32, v10
	v_ashrrev_i32_e32 v31, 31, v30
	v_lshlrev_b64 v[30:31], 12, v[30:31]
	v_lshl_add_u64 v[30:31], v[8:9], 0, v[30:31]
	global_load_dword v29, v[30:31], off nt
.LBB0_730:
	s_and_b64 vcc, exec, s[0:1]
	s_cbranch_vccnz .LBB0_732
	v_or_b32_e32 v30, 34, v10
	v_ashrrev_i32_e32 v31, 31, v30
	v_lshlrev_b64 v[30:31], 12, v[30:31]
	v_lshl_add_u64 v[30:31], v[8:9], 0, v[30:31]
	global_load_dword v28, v[30:31], off nt
.LBB0_732:
	v_mov_b32_e32 v30, 0
	s_and_b64 vcc, exec, s[0:1]
	v_mov_b32_e32 v31, 0
	s_cbranch_vccnz .LBB0_734
	v_or_b32_e32 v32, 36, v10
	v_ashrrev_i32_e32 v33, 31, v32
	v_lshlrev_b64 v[32:33], 12, v[32:33]
	v_lshl_add_u64 v[32:33], v[8:9], 0, v[32:33]
	global_load_dword v31, v[32:33], off nt
.LBB0_734:
	s_and_b64 vcc, exec, s[0:1]
	s_cbranch_vccnz .LBB0_736
	v_or_b32_e32 v32, 38, v10
	v_ashrrev_i32_e32 v33, 31, v32
	v_lshlrev_b64 v[32:33], 12, v[32:33]
	v_lshl_add_u64 v[32:33], v[8:9], 0, v[32:33]
	global_load_dword v30, v[32:33], off nt
.LBB0_736:
	v_mov_b32_e32 v32, 0
	s_and_b64 vcc, exec, s[0:1]
	v_mov_b32_e32 v33, 0
	s_cbranch_vccnz .LBB0_738
	v_or_b32_e32 v34, 40, v10
	v_ashrrev_i32_e32 v35, 31, v34
	v_lshlrev_b64 v[34:35], 12, v[34:35]
	v_lshl_add_u64 v[34:35], v[8:9], 0, v[34:35]
	global_load_dword v33, v[34:35], off nt
.LBB0_738:
	s_and_b64 vcc, exec, s[0:1]
	s_cbranch_vccnz .LBB0_740
	v_or_b32_e32 v34, 42, v10
	v_ashrrev_i32_e32 v35, 31, v34
	v_lshlrev_b64 v[34:35], 12, v[34:35]
	v_lshl_add_u64 v[34:35], v[8:9], 0, v[34:35]
	global_load_dword v32, v[34:35], off nt
.LBB0_740:
	v_mov_b32_e32 v34, 0
	s_and_b64 vcc, exec, s[0:1]
	v_mov_b32_e32 v35, 0
	s_cbranch_vccnz .LBB0_742
	v_or_b32_e32 v36, 44, v10
	v_ashrrev_i32_e32 v37, 31, v36
	v_lshlrev_b64 v[36:37], 12, v[36:37]
	v_lshl_add_u64 v[36:37], v[8:9], 0, v[36:37]
	global_load_dword v35, v[36:37], off nt
.LBB0_742:
	s_and_b64 vcc, exec, s[0:1]
	s_cbranch_vccnz .LBB0_744
	v_or_b32_e32 v36, 46, v10
	v_ashrrev_i32_e32 v37, 31, v36
	v_lshlrev_b64 v[36:37], 12, v[36:37]
	v_lshl_add_u64 v[36:37], v[8:9], 0, v[36:37]
	global_load_dword v34, v[36:37], off nt
.LBB0_744:
	v_mov_b32_e32 v36, 0
	s_and_b64 vcc, exec, s[0:1]
	v_mov_b32_e32 v37, 0
	s_cbranch_vccnz .LBB0_746
	v_or_b32_e32 v38, 48, v10
	v_ashrrev_i32_e32 v39, 31, v38
	v_lshlrev_b64 v[38:39], 12, v[38:39]
	v_lshl_add_u64 v[38:39], v[8:9], 0, v[38:39]
	global_load_dword v37, v[38:39], off nt
.LBB0_746:
	s_and_b64 vcc, exec, s[0:1]
	s_cbranch_vccnz .LBB0_748
	v_or_b32_e32 v38, 50, v10
	v_ashrrev_i32_e32 v39, 31, v38
	v_lshlrev_b64 v[38:39], 12, v[38:39]
	v_lshl_add_u64 v[38:39], v[8:9], 0, v[38:39]
	global_load_dword v36, v[38:39], off nt
.LBB0_748:
	v_mov_b32_e32 v38, 0
	s_and_b64 vcc, exec, s[0:1]
	v_mov_b32_e32 v39, 0
	s_cbranch_vccnz .LBB0_750
	v_or_b32_e32 v40, 52, v10
	s_waitcnt lgkmcnt(0)
	v_ashrrev_i32_e32 v41, 31, v40
	v_lshlrev_b64 v[40:41], 12, v[40:41]
	v_lshl_add_u64 v[40:41], v[8:9], 0, v[40:41]
	global_load_dword v39, v[40:41], off nt
.LBB0_750:
	s_and_b64 vcc, exec, s[0:1]
	s_cbranch_vccnz .LBB0_752
	v_or_b32_e32 v40, 54, v10
	s_waitcnt lgkmcnt(0)
	v_ashrrev_i32_e32 v41, 31, v40
	v_lshlrev_b64 v[40:41], 12, v[40:41]
	v_lshl_add_u64 v[40:41], v[8:9], 0, v[40:41]
	global_load_dword v38, v[40:41], off nt
.LBB0_752:
	v_mov_b32_e32 v40, 0
	s_and_b64 vcc, exec, s[0:1]
	s_waitcnt lgkmcnt(0)
	v_mov_b32_e32 v41, 0
	s_cbranch_vccnz .LBB0_754
	v_or_b32_e32 v42, 56, v10
	v_ashrrev_i32_e32 v43, 31, v42
	v_lshlrev_b64 v[42:43], 12, v[42:43]
	v_lshl_add_u64 v[42:43], v[8:9], 0, v[42:43]
	global_load_dword v41, v[42:43], off nt
.LBB0_754:
	s_and_b64 vcc, exec, s[0:1]
	s_cbranch_vccnz .LBB0_756
	v_or_b32_e32 v42, 58, v10
	v_ashrrev_i32_e32 v43, 31, v42
	v_lshlrev_b64 v[42:43], 12, v[42:43]
	v_lshl_add_u64 v[42:43], v[8:9], 0, v[42:43]
	global_load_dword v40, v[42:43], off nt
.LBB0_756:
	v_mov_b32_e32 v42, 0
	s_and_b64 vcc, exec, s[0:1]
	v_mov_b32_e32 v43, 0
	s_cbranch_vccnz .LBB0_758
	v_or_b32_e32 v44, 60, v10
	v_ashrrev_i32_e32 v45, 31, v44
	v_lshlrev_b64 v[44:45], 12, v[44:45]
	v_lshl_add_u64 v[44:45], v[8:9], 0, v[44:45]
	global_load_dword v43, v[44:45], off nt
.LBB0_758:
	s_and_b64 vcc, exec, s[0:1]
	s_cbranch_vccnz .LBB0_695
	v_or_b32_e32 v44, 62, v10
	v_ashrrev_i32_e32 v45, 31, v44
	v_lshlrev_b64 v[44:45], 12, v[44:45]
	v_lshl_add_u64 v[8:9], v[8:9], 0, v[44:45]
	global_load_dword v42, v[8:9], off nt
	s_branch .LBB0_695
